# prep adaLN modulation GEMV: 64 weight-row loads in flight per wave instead of 8 (unrolled, registers), plus attention epilogue LDS exchange reads batched
# speedup vs baseline: 1.0122x; 1.0122x over previous
; __device__ __forceinline__ float sigmoidf_(float v) { return __builtin_amdgcn_rcpf(1.f + __expf(-v)); }
; __device__ __forceinline__ void prep_phase(const Params& p, LAS unsigned char* lds) {
;     ...
;     for (int it = gw; it < 2 * 96 * 8; it += NGW) {
;         const int l = it / 768, r = it % 768, cgp = r >> 3, kc = r & 7;
;         const int col = cgp * 64 + lane, k0 = kc * 128;
;         float sv[9][2];
; #pragma unroll
;         for (int b = 0; b < 9; ++b)
; #pragma unroll
;             for (int hh = 0; hh < 2; ++hh) { const int k = k0 + hh * 64 + lane; const float cv = (b < 8) ? p.c[b * DM + k] : p.c_ctx[k]; sv[b][hh] = cv * sigmoidf_(cv); }
;         float ac[9];
; #pragma unroll
;         for (int b = 0; b < 9; ++b) ac[b] = 0.f;
;         const float* wp = p.w_ada + ((size_t)l * DM + k0) * 6144 + col;
; #pragma unroll
;         for (int hh = 0; hh < 2; ++hh) {
; #pragma unroll 8
;             for (int kk = 0; kk < 64; ++kk) {
;                 const float wv = wp[(size_t)(hh * 64 + kk) * 6144];
.LBB0_99:
	s_mov_b32 s0, 0x2aaaaaab
	v_mul_hi_i32 v1, v80, s0
	v_lshrrev_b32_e32 v2, 31, v1
	v_ashrrev_i32_e32 v1, 7, v1
	v_add_u32_e32 v1, v1, v2
	v_mul_i32_i24_e32 v2, 0x300, v1
	v_sub_u32_e32 v18, v80, v2
	v_and_b32_e32 v22, 7, v18
	v_readlane_b32 s56, v252, 16
	v_lshl_or_b32 v2, v22, 9, v81
	v_readlane_b32 s58, v252, 18
	v_readlane_b32 s59, v252, 19
	s_movk_i32 s0, 0x2000
	v_readlane_b32 s62, v252, 22
	v_lshl_add_u64 v[4:5], s[58:59], 0, v[2:3]
	v_add_co_u32_e32 v6, vcc, s0, v4
	s_movk_i32 s0, 0x4000
	s_nop 0
	v_addc_co_u32_e32 v7, vcc, 0, v5, vcc
	v_add_co_u32_e32 v8, vcc, s0, v4
	s_movk_i32 s0, 0x7000
	s_nop 0
	v_addc_co_u32_e32 v9, vcc, 0, v5, vcc
	v_add_co_u32_e32 v10, vcc, s3, v4
	v_readlane_b32 s63, v252, 23
	s_nop 0
	v_addc_co_u32_e32 v11, vcc, 0, v5, vcc
	v_add_co_u32_e32 v12, vcc, s0, v4
	s_movk_i32 s0, 0x1000
	s_nop 0
	v_addc_co_u32_e32 v13, vcc, 0, v5, vcc
	v_add_co_u32_e32 v14, vcc, s0, v4
	global_load_dword v19, v2, s[58:59]
	global_load_dword v20, v2, s[62:63]
	global_load_dword v21, v[6:7], off offset:-4096
	global_load_dword v35, v[6:7], off
	global_load_dword v36, v[8:9], off offset:-4096
	global_load_dword v37, v[8:9], off
	global_load_dword v38, v[10:11], off offset:-4096
	global_load_dword v39, v[10:11], off
	global_load_dword v40, v[12:13], off
	s_movk_i32 s1, 0x3000
	v_addc_co_u32_e32 v15, vcc, 0, v5, vcc
	v_add_co_u32_e32 v16, vcc, s1, v4
	s_movk_i32 s12, 0x5000
	s_nop 0
	v_addc_co_u32_e32 v17, vcc, 0, v5, vcc
	v_add_co_u32_e32 v4, vcc, s12, v4
	s_mov_b32 s0, 0x1800000
	s_nop 0
	v_addc_co_u32_e32 v5, vcc, 0, v5, vcc
	global_load_dword v23, v[10:11], off offset:256
	global_load_dword v24, v[8:9], off offset:256
	global_load_dword v26, v[6:7], off offset:256
	global_load_dword v29, v2, s[58:59] offset:256
	global_load_dword v25, v2, s[62:63] offset:256
	global_load_dword v31, v[14:15], off offset:256
	global_load_dword v30, v[16:17], off offset:256
	global_load_dword v27, v[12:13], off offset:256
	global_load_dword v32, v[4:5], off offset:256
	v_lshlrev_b32_e32 v2, 3, v18
	v_and_b32_e32 v28, 0xffffffc0, v2
	s_mov_b32 s26, 0
	v_mov_b32_e32 v12, 0
	v_mov_b32_e32 v13, v3
	v_readlane_b32 s57, v252, 17
	v_readlane_b32 s60, v252, 20
	v_readlane_b32 s61, v252, 21
	v_readlane_b32 s64, v252, 24
	v_readlane_b32 s65, v252, 25
	v_readlane_b32 s66, v252, 26
	v_readlane_b32 s67, v252, 27
	v_readlane_b32 s68, v252, 28
	v_readlane_b32 s69, v252, 29
	v_readlane_b32 s70, v252, 30
	v_readlane_b32 s71, v252, 31
	s_waitcnt vmcnt(17)
	v_mul_f32_e32 v2, 0xbfb8aa3b, v19
	s_waitcnt vmcnt(16)
	v_mul_f32_e32 v4, 0xbfb8aa3b, v20
	v_exp_f32_e32 v2, v2
	s_waitcnt vmcnt(14)
	v_mul_f32_e32 v6, 0xbfb8aa3b, v35
	s_waitcnt vmcnt(13)
	v_mul_f32_e32 v7, 0xbfb8aa3b, v36
	v_exp_f32_e32 v4, v4
	v_mul_f32_e32 v5, 0xbfb8aa3b, v21
	v_exp_f32_e32 v6, v6
	v_exp_f32_e32 v7, v7
	v_exp_f32_e32 v5, v5
	s_waitcnt vmcnt(12)
	v_mul_f32_e32 v8, 0xbfb8aa3b, v37
	s_waitcnt vmcnt(11)
	v_mul_f32_e32 v9, 0xbfb8aa3b, v38
	s_waitcnt vmcnt(10)
	v_mul_f32_e32 v10, 0xbfb8aa3b, v39
	s_waitcnt vmcnt(9)
	v_mul_f32_e32 v11, 0xbfb8aa3b, v40
	v_exp_f32_e32 v8, v8
	v_exp_f32_e32 v9, v9
	v_exp_f32_e32 v10, v10
	v_exp_f32_e32 v11, v11
	v_add_f32_e32 v2, 1.0, v2
	v_add_f32_e32 v4, 1.0, v4
	v_rcp_f32_e32 v2, v2
	v_add_f32_e32 v6, 1.0, v6
	v_add_f32_e32 v7, 1.0, v7
	v_rcp_f32_e32 v4, v4
	v_add_f32_e32 v5, 1.0, v5
	v_rcp_f32_e32 v6, v6
	v_rcp_f32_e32 v7, v7
	v_rcp_f32_e32 v5, v5
	v_add_f32_e32 v8, 1.0, v8
	v_add_f32_e32 v9, 1.0, v9
	v_add_f32_e32 v10, 1.0, v10
	v_add_f32_e32 v11, 1.0, v11
	v_rcp_f32_e32 v8, v8
	v_rcp_f32_e32 v9, v9
	v_rcp_f32_e32 v10, v10
	v_rcp_f32_e32 v11, v11
	v_mul_f32_e32 v33, v19, v2
	v_and_b32_e32 v2, 7, v80
	v_mul_f32_e32 v35, v35, v6
	v_mul_f32_e32 v36, v36, v7
	v_mul_f32_e32 v41, v20, v4
	v_or_b32_e32 v4, v28, v67
	v_mul_hi_u32_u24_e32 v7, 0x300000, v2
	v_mul_u32_u24_e32 v6, 0x300000, v2
	v_mul_f32_e32 v34, v21, v5
	v_ashrrev_i32_e32 v5, 31, v4
	v_mad_i64_i32 v[14:15], s[0:1], v1, s0, v[6:7]
	v_lshl_add_u64 v[6:7], v[4:5], 2, v[14:15]
	v_mul_f32_e32 v37, v37, v8
	v_mul_f32_e32 v38, v38, v9
	v_mul_f32_e32 v39, v39, v10
	v_mul_f32_e32 v40, v40, v11
	v_lshl_add_u64 v[16:17], s[8:9], 0, v[6:7]
	v_mov_b32_e32 v10, 0
	v_mov_b32_e32 v11, v3
	v_mov_b32_e32 v8, 0
	v_mov_b32_e32 v9, v3
	v_mov_b32_e32 v6, 0
	v_mov_b32_e32 v7, v3
	v_mov_b32_e32 v2, 0
	s_mov_b32 s100, 0xfffe8000
	s_mov_b32 s101, -1
	v_lshl_add_u64 v[246:247], v[16:17], 0, s[100:101]
	s_mov_b32 s100, 0x6000
	s_mov_b32 s101, 0
	global_load_dword v82, v[246:247], off
	v_lshl_add_u64 v[246:247], v[246:247], 0, s[100:101]
	global_load_dword v84, v[246:247], off
	v_lshl_add_u64 v[246:247], v[246:247], 0, s[100:101]
	global_load_dword v86, v[246:247], off
	v_lshl_add_u64 v[246:247], v[246:247], 0, s[100:101]
	global_load_dword v88, v[246:247], off
	v_lshl_add_u64 v[246:247], v[246:247], 0, s[100:101]
	global_load_dword v90, v[246:247], off
	v_lshl_add_u64 v[246:247], v[246:247], 0, s[100:101]
	global_load_dword v92, v[246:247], off
	v_lshl_add_u64 v[246:247], v[246:247], 0, s[100:101]
	global_load_dword v94, v[246:247], off
	v_lshl_add_u64 v[246:247], v[246:247], 0, s[100:101]
	global_load_dword v96, v[246:247], off
	v_lshl_add_u64 v[246:247], v[246:247], 0, s[100:101]
	global_load_dword v98, v[246:247], off
	v_lshl_add_u64 v[246:247], v[246:247], 0, s[100:101]
	global_load_dword v100, v[246:247], off
	v_lshl_add_u64 v[246:247], v[246:247], 0, s[100:101]
	global_load_dword v102, v[246:247], off
	v_lshl_add_u64 v[246:247], v[246:247], 0, s[100:101]
	global_load_dword v104, v[246:247], off
	v_lshl_add_u64 v[246:247], v[246:247], 0, s[100:101]
	global_load_dword v106, v[246:247], off
	v_lshl_add_u64 v[246:247], v[246:247], 0, s[100:101]
; __device__ __forceinline__ void prep_phase(const Params& p, LAS unsigned char* lds) {
;     ...
;         for (int hh = 0; hh < 2; ++hh) {
; #pragma unroll 8
;             for (int kk = 0; kk < 64; ++kk) {
;                 const float wv = wp[(size_t)(hh * 64 + kk) * 6144];
; #pragma unroll
;                 for (int b = 0; b < 9; ++b) ac[b] += __int_as_float(__builtin_amdgcn_readlane(__float_as_int(sv[b][hh]), kk)) * wv;
	global_load_dword v108, v[246:247], off
	v_lshl_add_u64 v[246:247], v[246:247], 0, s[100:101]
	global_load_dword v110, v[246:247], off
	v_lshl_add_u64 v[246:247], v[246:247], 0, s[100:101]
	global_load_dword v112, v[246:247], off
	v_lshl_add_u64 v[246:247], v[246:247], 0, s[100:101]
	global_load_dword v114, v[246:247], off
	v_lshl_add_u64 v[246:247], v[246:247], 0, s[100:101]
	global_load_dword v116, v[246:247], off
	v_lshl_add_u64 v[246:247], v[246:247], 0, s[100:101]
	global_load_dword v118, v[246:247], off
	v_lshl_add_u64 v[246:247], v[246:247], 0, s[100:101]
	global_load_dword v120, v[246:247], off
	v_lshl_add_u64 v[246:247], v[246:247], 0, s[100:101]
	global_load_dword v122, v[246:247], off
	v_lshl_add_u64 v[246:247], v[246:247], 0, s[100:101]
	global_load_dword v124, v[246:247], off
	v_lshl_add_u64 v[246:247], v[246:247], 0, s[100:101]
	global_load_dword v126, v[246:247], off
	v_lshl_add_u64 v[246:247], v[246:247], 0, s[100:101]
	global_load_dword v128, v[246:247], off
	v_lshl_add_u64 v[246:247], v[246:247], 0, s[100:101]
	global_load_dword v130, v[246:247], off
	v_lshl_add_u64 v[246:247], v[246:247], 0, s[100:101]
	global_load_dword v132, v[246:247], off
	v_lshl_add_u64 v[246:247], v[246:247], 0, s[100:101]
	global_load_dword v134, v[246:247], off
	v_lshl_add_u64 v[246:247], v[246:247], 0, s[100:101]
	global_load_dword v136, v[246:247], off
	v_lshl_add_u64 v[246:247], v[246:247], 0, s[100:101]
	global_load_dword v138, v[246:247], off
	v_lshl_add_u64 v[246:247], v[246:247], 0, s[100:101]
	global_load_dword v140, v[246:247], off
	v_lshl_add_u64 v[246:247], v[246:247], 0, s[100:101]
	global_load_dword v142, v[246:247], off
	v_lshl_add_u64 v[246:247], v[246:247], 0, s[100:101]
	global_load_dword v144, v[246:247], off
	v_lshl_add_u64 v[246:247], v[246:247], 0, s[100:101]
	global_load_dword v146, v[246:247], off
	v_lshl_add_u64 v[246:247], v[246:247], 0, s[100:101]
	global_load_dword v148, v[246:247], off
	v_lshl_add_u64 v[246:247], v[246:247], 0, s[100:101]
	global_load_dword v150, v[246:247], off
	v_lshl_add_u64 v[246:247], v[246:247], 0, s[100:101]
	global_load_dword v152, v[246:247], off
	v_lshl_add_u64 v[246:247], v[246:247], 0, s[100:101]
	global_load_dword v154, v[246:247], off
	v_lshl_add_u64 v[246:247], v[246:247], 0, s[100:101]
	global_load_dword v158, v[246:247], off
	v_lshl_add_u64 v[246:247], v[246:247], 0, s[100:101]
	global_load_dword v160, v[246:247], off
	v_lshl_add_u64 v[246:247], v[246:247], 0, s[100:101]
	global_load_dword v162, v[246:247], off
	v_lshl_add_u64 v[246:247], v[246:247], 0, s[100:101]
	global_load_dword v164, v[246:247], off
	v_lshl_add_u64 v[246:247], v[246:247], 0, s[100:101]
	global_load_dword v166, v[246:247], off
	v_lshl_add_u64 v[246:247], v[246:247], 0, s[100:101]
	global_load_dword v168, v[246:247], off
	v_lshl_add_u64 v[246:247], v[246:247], 0, s[100:101]
	global_load_dword v170, v[246:247], off
	v_lshl_add_u64 v[246:247], v[246:247], 0, s[100:101]
	global_load_dword v172, v[246:247], off
	v_lshl_add_u64 v[246:247], v[246:247], 0, s[100:101]
	global_load_dword v174, v[246:247], off
	v_lshl_add_u64 v[246:247], v[246:247], 0, s[100:101]
	global_load_dword v176, v[246:247], off
	v_lshl_add_u64 v[246:247], v[246:247], 0, s[100:101]
	global_load_dword v178, v[246:247], off
	v_lshl_add_u64 v[246:247], v[246:247], 0, s[100:101]
	global_load_dword v180, v[246:247], off
	v_lshl_add_u64 v[246:247], v[246:247], 0, s[100:101]
	global_load_dword v182, v[246:247], off
	v_lshl_add_u64 v[246:247], v[246:247], 0, s[100:101]
	global_load_dword v184, v[246:247], off
	v_lshl_add_u64 v[246:247], v[246:247], 0, s[100:101]
	global_load_dword v186, v[246:247], off
	v_lshl_add_u64 v[246:247], v[246:247], 0, s[100:101]
	global_load_dword v188, v[246:247], off
	v_lshl_add_u64 v[246:247], v[246:247], 0, s[100:101]
	global_load_dword v190, v[246:247], off
	v_lshl_add_u64 v[246:247], v[246:247], 0, s[100:101]
	global_load_dword v194, v[246:247], off
	v_lshl_add_u64 v[246:247], v[246:247], 0, s[100:101]
	global_load_dword v196, v[246:247], off
	v_lshl_add_u64 v[246:247], v[246:247], 0, s[100:101]
	global_load_dword v198, v[246:247], off
	v_lshl_add_u64 v[246:247], v[246:247], 0, s[100:101]
	global_load_dword v202, v[246:247], off
	v_lshl_add_u64 v[246:247], v[246:247], 0, s[100:101]
	global_load_dword v204, v[246:247], off
	v_lshl_add_u64 v[246:247], v[246:247], 0, s[100:101]
	global_load_dword v206, v[246:247], off
	v_lshl_add_u64 v[246:247], v[246:247], 0, s[100:101]
	global_load_dword v208, v[246:247], off
	v_lshl_add_u64 v[246:247], v[246:247], 0, s[100:101]
	global_load_dword v210, v[246:247], off
	v_lshl_add_u64 v[246:247], v[246:247], 0, s[100:101]
	global_load_dword v212, v[246:247], off
	v_lshl_add_u64 v[246:247], v[246:247], 0, s[100:101]
	global_load_dword v214, v[246:247], off
	v_lshl_add_u64 v[246:247], v[246:247], 0, s[100:101]
	v_readlane_b32 s18, v33, 0
	v_readlane_b32 s19, v34, 0
	v_readlane_b32 s20, v35, 0
	v_readlane_b32 s21, v36, 0
	v_readlane_b32 s22, v37, 0
	v_readlane_b32 s23, v38, 0
	v_readlane_b32 s24, v39, 0
	v_readlane_b32 s25, v40, 0
	v_readlane_b32 s54, v41, 0
	v_readlane_b32 s0, v33, 1
	v_readlane_b32 s1, v34, 1
	v_readlane_b32 s26, v35, 1
	v_readlane_b32 s27, v36, 1
	v_readlane_b32 s28, v37, 1
	v_readlane_b32 s29, v38, 1
	v_readlane_b32 s30, v39, 1
	v_readlane_b32 s31, v40, 1
	v_readlane_b32 s87, v41, 1
	v_readlane_b32 s34, v33, 2
	v_readlane_b32 s35, v34, 2
	v_readlane_b32 s36, v35, 2
	v_readlane_b32 s37, v36, 2
	v_readlane_b32 s38, v37, 2
	v_readlane_b32 s39, v38, 2
	v_readlane_b32 s40, v39, 2
	v_readlane_b32 s41, v40, 2
	v_readlane_b32 s88, v41, 2
	v_readlane_b32 s42, v33, 3
	v_readlane_b32 s43, v34, 3
	v_readlane_b32 s44, v35, 3
	v_readlane_b32 s45, v36, 3
	v_readlane_b32 s46, v37, 3
	v_readlane_b32 s47, v38, 3
	v_readlane_b32 s48, v39, 3
	v_readlane_b32 s49, v40, 3
	v_readlane_b32 s55, v41, 3
	v_readlane_b32 s58, v33, 4
	v_readlane_b32 s59, v34, 4
	v_readlane_b32 s60, v35, 4
	v_readlane_b32 s61, v36, 4
	v_readlane_b32 s62, v37, 4
	v_readlane_b32 s63, v38, 4
	v_readlane_b32 s64, v39, 4
	v_readlane_b32 s65, v40, 4
	v_readlane_b32 s89, v41, 4
	v_readlane_b32 s56, v33, 5
	v_readlane_b32 s57, v34, 5
	v_readlane_b32 s66, v35, 5
	v_readlane_b32 s67, v36, 5
	v_readlane_b32 s68, v37, 5
	v_readlane_b32 s69, v38, 5
	v_readlane_b32 s70, v39, 5
	v_readlane_b32 s71, v40, 5
	v_readlane_b32 s90, v41, 5
	v_readlane_b32 s12, v33, 6
	v_readlane_b32 s13, v34, 6
	v_readlane_b32 s72, v35, 6
	v_readlane_b32 s73, v36, 6
	v_readlane_b32 s74, v37, 6
	v_readlane_b32 s75, v38, 6
	v_readlane_b32 s76, v39, 6
	v_readlane_b32 s77, v40, 6
	v_readlane_b32 s50, v41, 6
	v_readlane_b32 s78, v33, 7
	v_readlane_b32 s79, v34, 7
	v_readlane_b32 s80, v35, 7
	v_readlane_b32 s81, v36, 7
	v_readlane_b32 s82, v37, 7
	v_readlane_b32 s83, v38, 7
	v_readlane_b32 s84, v39, 7
	v_readlane_b32 s85, v40, 7
	v_readlane_b32 s86, v41, 7
	s_waitcnt vmcnt(56)
; __device__ __forceinline__ void prep_phase(const Params& p, LAS unsigned char* lds) {
;     ...
;         for (int hh = 0; hh < 2; ++hh) {
; #pragma unroll 8
;             for (int kk = 0; kk < 64; ++kk) {
;                 const float wv = wp[(size_t)(hh * 64 + kk) * 6144];
; #pragma unroll
;                 for (int b = 0; b < 9; ++b) ac[b] += __int_as_float(__builtin_amdgcn_readlane(__float_as_int(sv[b][hh]), kk)) * wv;
	v_pk_fma_f32 v[12:13], v[82:83], s[18:19], v[12:13] op_sel_hi:[0,1,1]
	v_pk_fma_f32 v[10:11], v[82:83], s[20:21], v[10:11] op_sel_hi:[0,1,1]
	v_pk_fma_f32 v[8:9], v[82:83], s[22:23], v[8:9] op_sel_hi:[0,1,1]
	v_pk_fma_f32 v[6:7], v[82:83], s[24:25], v[6:7] op_sel_hi:[0,1,1]
	v_fmac_f32_e32 v2, s54, v82
	v_pk_fma_f32 v[12:13], v[84:85], s[0:1], v[12:13] op_sel_hi:[0,1,1]
	v_pk_fma_f32 v[10:11], v[84:85], s[26:27], v[10:11] op_sel_hi:[0,1,1]
	v_pk_fma_f32 v[8:9], v[84:85], s[28:29], v[8:9] op_sel_hi:[0,1,1]
	v_pk_fma_f32 v[6:7], v[84:85], s[30:31], v[6:7] op_sel_hi:[0,1,1]
	v_fmac_f32_e32 v2, s87, v84
	v_pk_fma_f32 v[12:13], v[86:87], s[34:35], v[12:13] op_sel_hi:[0,1,1]
	v_pk_fma_f32 v[10:11], v[86:87], s[36:37], v[10:11] op_sel_hi:[0,1,1]
	v_pk_fma_f32 v[8:9], v[86:87], s[38:39], v[8:9] op_sel_hi:[0,1,1]
	v_pk_fma_f32 v[6:7], v[86:87], s[40:41], v[6:7] op_sel_hi:[0,1,1]
	v_fmac_f32_e32 v2, s88, v86
	v_pk_fma_f32 v[12:13], v[88:89], s[42:43], v[12:13] op_sel_hi:[0,1,1]
	v_pk_fma_f32 v[10:11], v[88:89], s[44:45], v[10:11] op_sel_hi:[0,1,1]
	v_pk_fma_f32 v[8:9], v[88:89], s[46:47], v[8:9] op_sel_hi:[0,1,1]
	v_pk_fma_f32 v[6:7], v[88:89], s[48:49], v[6:7] op_sel_hi:[0,1,1]
	v_fmac_f32_e32 v2, s55, v88
	v_pk_fma_f32 v[12:13], v[90:91], s[58:59], v[12:13] op_sel_hi:[0,1,1]
	v_pk_fma_f32 v[10:11], v[90:91], s[60:61], v[10:11] op_sel_hi:[0,1,1]
	v_pk_fma_f32 v[8:9], v[90:91], s[62:63], v[8:9] op_sel_hi:[0,1,1]
	v_pk_fma_f32 v[6:7], v[90:91], s[64:65], v[6:7] op_sel_hi:[0,1,1]
	v_fmac_f32_e32 v2, s89, v90
	v_pk_fma_f32 v[12:13], v[92:93], s[56:57], v[12:13] op_sel_hi:[0,1,1]
	v_pk_fma_f32 v[10:11], v[92:93], s[66:67], v[10:11] op_sel_hi:[0,1,1]
	v_pk_fma_f32 v[8:9], v[92:93], s[68:69], v[8:9] op_sel_hi:[0,1,1]
	v_pk_fma_f32 v[6:7], v[92:93], s[70:71], v[6:7] op_sel_hi:[0,1,1]
	v_fmac_f32_e32 v2, s90, v92
	v_pk_fma_f32 v[12:13], v[94:95], s[12:13], v[12:13] op_sel_hi:[0,1,1]
	v_pk_fma_f32 v[10:11], v[94:95], s[72:73], v[10:11] op_sel_hi:[0,1,1]
	v_pk_fma_f32 v[8:9], v[94:95], s[74:75], v[8:9] op_sel_hi:[0,1,1]
	v_pk_fma_f32 v[6:7], v[94:95], s[76:77], v[6:7] op_sel_hi:[0,1,1]
	v_fmac_f32_e32 v2, s50, v94
	v_pk_fma_f32 v[12:13], v[96:97], s[78:79], v[12:13] op_sel_hi:[0,1,1]
	v_pk_fma_f32 v[10:11], v[96:97], s[80:81], v[10:11] op_sel_hi:[0,1,1]
	v_pk_fma_f32 v[8:9], v[96:97], s[82:83], v[8:9] op_sel_hi:[0,1,1]
	v_pk_fma_f32 v[6:7], v[96:97], s[84:85], v[6:7] op_sel_hi:[0,1,1]
	v_fmac_f32_e32 v2, s86, v96
	global_load_dword v82, v[246:247], off
	v_lshl_add_u64 v[246:247], v[246:247], 0, s[100:101]
	global_load_dword v84, v[246:247], off
	v_lshl_add_u64 v[246:247], v[246:247], 0, s[100:101]
	global_load_dword v86, v[246:247], off
	v_lshl_add_u64 v[246:247], v[246:247], 0, s[100:101]
	global_load_dword v88, v[246:247], off
	v_lshl_add_u64 v[246:247], v[246:247], 0, s[100:101]
	global_load_dword v90, v[246:247], off
	v_lshl_add_u64 v[246:247], v[246:247], 0, s[100:101]
	global_load_dword v92, v[246:247], off
	v_lshl_add_u64 v[246:247], v[246:247], 0, s[100:101]
	global_load_dword v94, v[246:247], off
	v_lshl_add_u64 v[246:247], v[246:247], 0, s[100:101]
	global_load_dword v96, v[246:247], off
	v_lshl_add_u64 v[246:247], v[246:247], 0, s[100:101]
	v_readlane_b32 s18, v33, 8
	v_readlane_b32 s19, v34, 8
	v_readlane_b32 s20, v35, 8
	v_readlane_b32 s21, v36, 8
	v_readlane_b32 s22, v37, 8
	v_readlane_b32 s23, v38, 8
	v_readlane_b32 s24, v39, 8
	v_readlane_b32 s25, v40, 8
	v_readlane_b32 s54, v41, 8
	v_readlane_b32 s0, v33, 9
	v_readlane_b32 s1, v34, 9
	v_readlane_b32 s26, v35, 9
	v_readlane_b32 s27, v36, 9
	v_readlane_b32 s28, v37, 9
	v_readlane_b32 s29, v38, 9
	v_readlane_b32 s30, v39, 9
	v_readlane_b32 s31, v40, 9
	v_readlane_b32 s87, v41, 9
	v_readlane_b32 s34, v33, 10
	v_readlane_b32 s35, v34, 10
	v_readlane_b32 s36, v35, 10
	v_readlane_b32 s37, v36, 10
	v_readlane_b32 s38, v37, 10
	v_readlane_b32 s39, v38, 10
	v_readlane_b32 s40, v39, 10
	v_readlane_b32 s41, v40, 10
	v_readlane_b32 s88, v41, 10
	v_readlane_b32 s42, v33, 11
	v_readlane_b32 s43, v34, 11
	v_readlane_b32 s44, v35, 11
	v_readlane_b32 s45, v36, 11
	v_readlane_b32 s46, v37, 11
	v_readlane_b32 s47, v38, 11
	v_readlane_b32 s48, v39, 11
	v_readlane_b32 s49, v40, 11
	v_readlane_b32 s55, v41, 11
	v_readlane_b32 s58, v33, 12
	v_readlane_b32 s59, v34, 12
	v_readlane_b32 s60, v35, 12
	v_readlane_b32 s61, v36, 12
	v_readlane_b32 s62, v37, 12
	v_readlane_b32 s63, v38, 12
	v_readlane_b32 s64, v39, 12
	v_readlane_b32 s65, v40, 12
	v_readlane_b32 s89, v41, 12
	v_readlane_b32 s56, v33, 13
	v_readlane_b32 s57, v34, 13
	v_readlane_b32 s66, v35, 13
	v_readlane_b32 s67, v36, 13
	v_readlane_b32 s68, v37, 13
	v_readlane_b32 s69, v38, 13
	v_readlane_b32 s70, v39, 13
	v_readlane_b32 s71, v40, 13
	v_readlane_b32 s90, v41, 13
	v_readlane_b32 s12, v33, 14
	v_readlane_b32 s13, v34, 14
	v_readlane_b32 s72, v35, 14
	v_readlane_b32 s73, v36, 14
	v_readlane_b32 s74, v37, 14
	v_readlane_b32 s75, v38, 14
	v_readlane_b32 s76, v39, 14
	v_readlane_b32 s77, v40, 14
	v_readlane_b32 s50, v41, 14
	v_readlane_b32 s78, v33, 15
	v_readlane_b32 s79, v34, 15
	v_readlane_b32 s80, v35, 15
	v_readlane_b32 s81, v36, 15
	v_readlane_b32 s82, v37, 15
	v_readlane_b32 s83, v38, 15
	v_readlane_b32 s84, v39, 15
	v_readlane_b32 s85, v40, 15
	v_readlane_b32 s86, v41, 15
	s_waitcnt vmcnt(56)
; __device__ __forceinline__ void prep_phase(const Params& p, LAS unsigned char* lds) {
;     ...
;         for (int hh = 0; hh < 2; ++hh) {
; #pragma unroll 8
;             for (int kk = 0; kk < 64; ++kk) {
;                 const float wv = wp[(size_t)(hh * 64 + kk) * 6144];
; #pragma unroll
;                 for (int b = 0; b < 9; ++b) ac[b] += __int_as_float(__builtin_amdgcn_readlane(__float_as_int(sv[b][hh]), kk)) * wv;
	v_pk_fma_f32 v[12:13], v[98:99], s[18:19], v[12:13] op_sel_hi:[0,1,1]
	v_pk_fma_f32 v[10:11], v[98:99], s[20:21], v[10:11] op_sel_hi:[0,1,1]
	v_pk_fma_f32 v[8:9], v[98:99], s[22:23], v[8:9] op_sel_hi:[0,1,1]
	v_pk_fma_f32 v[6:7], v[98:99], s[24:25], v[6:7] op_sel_hi:[0,1,1]
	v_fmac_f32_e32 v2, s54, v98
	v_pk_fma_f32 v[12:13], v[100:101], s[0:1], v[12:13] op_sel_hi:[0,1,1]
	v_pk_fma_f32 v[10:11], v[100:101], s[26:27], v[10:11] op_sel_hi:[0,1,1]
	v_pk_fma_f32 v[8:9], v[100:101], s[28:29], v[8:9] op_sel_hi:[0,1,1]
	v_pk_fma_f32 v[6:7], v[100:101], s[30:31], v[6:7] op_sel_hi:[0,1,1]
	v_fmac_f32_e32 v2, s87, v100
	v_pk_fma_f32 v[12:13], v[102:103], s[34:35], v[12:13] op_sel_hi:[0,1,1]
	v_pk_fma_f32 v[10:11], v[102:103], s[36:37], v[10:11] op_sel_hi:[0,1,1]
	v_pk_fma_f32 v[8:9], v[102:103], s[38:39], v[8:9] op_sel_hi:[0,1,1]
	v_pk_fma_f32 v[6:7], v[102:103], s[40:41], v[6:7] op_sel_hi:[0,1,1]
	v_fmac_f32_e32 v2, s88, v102
	v_pk_fma_f32 v[12:13], v[104:105], s[42:43], v[12:13] op_sel_hi:[0,1,1]
	v_pk_fma_f32 v[10:11], v[104:105], s[44:45], v[10:11] op_sel_hi:[0,1,1]
	v_pk_fma_f32 v[8:9], v[104:105], s[46:47], v[8:9] op_sel_hi:[0,1,1]
	v_pk_fma_f32 v[6:7], v[104:105], s[48:49], v[6:7] op_sel_hi:[0,1,1]
	v_fmac_f32_e32 v2, s55, v104
	v_pk_fma_f32 v[12:13], v[106:107], s[58:59], v[12:13] op_sel_hi:[0,1,1]
	v_pk_fma_f32 v[10:11], v[106:107], s[60:61], v[10:11] op_sel_hi:[0,1,1]
	v_pk_fma_f32 v[8:9], v[106:107], s[62:63], v[8:9] op_sel_hi:[0,1,1]
	v_pk_fma_f32 v[6:7], v[106:107], s[64:65], v[6:7] op_sel_hi:[0,1,1]
	v_fmac_f32_e32 v2, s89, v106
	v_pk_fma_f32 v[12:13], v[108:109], s[56:57], v[12:13] op_sel_hi:[0,1,1]
	v_pk_fma_f32 v[10:11], v[108:109], s[66:67], v[10:11] op_sel_hi:[0,1,1]
	v_pk_fma_f32 v[8:9], v[108:109], s[68:69], v[8:9] op_sel_hi:[0,1,1]
	v_pk_fma_f32 v[6:7], v[108:109], s[70:71], v[6:7] op_sel_hi:[0,1,1]
	v_fmac_f32_e32 v2, s90, v108
	v_pk_fma_f32 v[12:13], v[110:111], s[12:13], v[12:13] op_sel_hi:[0,1,1]
	v_pk_fma_f32 v[10:11], v[110:111], s[72:73], v[10:11] op_sel_hi:[0,1,1]
	v_pk_fma_f32 v[8:9], v[110:111], s[74:75], v[8:9] op_sel_hi:[0,1,1]
	v_pk_fma_f32 v[6:7], v[110:111], s[76:77], v[6:7] op_sel_hi:[0,1,1]
	v_fmac_f32_e32 v2, s50, v110
	v_pk_fma_f32 v[12:13], v[112:113], s[78:79], v[12:13] op_sel_hi:[0,1,1]
	v_pk_fma_f32 v[10:11], v[112:113], s[80:81], v[10:11] op_sel_hi:[0,1,1]
	v_pk_fma_f32 v[8:9], v[112:113], s[82:83], v[8:9] op_sel_hi:[0,1,1]
	v_pk_fma_f32 v[6:7], v[112:113], s[84:85], v[6:7] op_sel_hi:[0,1,1]
	v_fmac_f32_e32 v2, s86, v112
	global_load_dword v98, v[246:247], off
	v_lshl_add_u64 v[246:247], v[246:247], 0, s[100:101]
	global_load_dword v100, v[246:247], off
	v_lshl_add_u64 v[246:247], v[246:247], 0, s[100:101]
	global_load_dword v102, v[246:247], off
	v_lshl_add_u64 v[246:247], v[246:247], 0, s[100:101]
	global_load_dword v104, v[246:247], off
	v_lshl_add_u64 v[246:247], v[246:247], 0, s[100:101]
	global_load_dword v106, v[246:247], off
	v_lshl_add_u64 v[246:247], v[246:247], 0, s[100:101]
	global_load_dword v108, v[246:247], off
	v_lshl_add_u64 v[246:247], v[246:247], 0, s[100:101]
	global_load_dword v110, v[246:247], off
	v_lshl_add_u64 v[246:247], v[246:247], 0, s[100:101]
	global_load_dword v112, v[246:247], off
	v_lshl_add_u64 v[246:247], v[246:247], 0, s[100:101]
	v_readlane_b32 s18, v33, 16
	v_readlane_b32 s19, v34, 16
	v_readlane_b32 s20, v35, 16
	v_readlane_b32 s21, v36, 16
	v_readlane_b32 s22, v37, 16
	v_readlane_b32 s23, v38, 16
	v_readlane_b32 s24, v39, 16
	v_readlane_b32 s25, v40, 16
	v_readlane_b32 s54, v41, 16
	v_readlane_b32 s0, v33, 17
	v_readlane_b32 s1, v34, 17
	v_readlane_b32 s26, v35, 17
	v_readlane_b32 s27, v36, 17
	v_readlane_b32 s28, v37, 17
	v_readlane_b32 s29, v38, 17
	v_readlane_b32 s30, v39, 17
	v_readlane_b32 s31, v40, 17
	v_readlane_b32 s87, v41, 17
	v_readlane_b32 s34, v33, 18
	v_readlane_b32 s35, v34, 18
	v_readlane_b32 s36, v35, 18
	v_readlane_b32 s37, v36, 18
	v_readlane_b32 s38, v37, 18
	v_readlane_b32 s39, v38, 18
	v_readlane_b32 s40, v39, 18
	v_readlane_b32 s41, v40, 18
	v_readlane_b32 s88, v41, 18
	v_readlane_b32 s42, v33, 19
	v_readlane_b32 s43, v34, 19
	v_readlane_b32 s44, v35, 19
	v_readlane_b32 s45, v36, 19
	v_readlane_b32 s46, v37, 19
	v_readlane_b32 s47, v38, 19
	v_readlane_b32 s48, v39, 19
	v_readlane_b32 s49, v40, 19
	v_readlane_b32 s55, v41, 19
	v_readlane_b32 s58, v33, 20
	v_readlane_b32 s59, v34, 20
	v_readlane_b32 s60, v35, 20
	v_readlane_b32 s61, v36, 20
	v_readlane_b32 s62, v37, 20
	v_readlane_b32 s63, v38, 20
	v_readlane_b32 s64, v39, 20
	v_readlane_b32 s65, v40, 20
	v_readlane_b32 s89, v41, 20
	v_readlane_b32 s56, v33, 21
	v_readlane_b32 s57, v34, 21
	v_readlane_b32 s66, v35, 21
	v_readlane_b32 s67, v36, 21
	v_readlane_b32 s68, v37, 21
	v_readlane_b32 s69, v38, 21
	v_readlane_b32 s70, v39, 21
	v_readlane_b32 s71, v40, 21
	v_readlane_b32 s90, v41, 21
	v_readlane_b32 s12, v33, 22
	v_readlane_b32 s13, v34, 22
	v_readlane_b32 s72, v35, 22
	v_readlane_b32 s73, v36, 22
	v_readlane_b32 s74, v37, 22
	v_readlane_b32 s75, v38, 22
	v_readlane_b32 s76, v39, 22
	v_readlane_b32 s77, v40, 22
	v_readlane_b32 s50, v41, 22
	v_readlane_b32 s78, v33, 23
	v_readlane_b32 s79, v34, 23
	v_readlane_b32 s80, v35, 23
	v_readlane_b32 s81, v36, 23
	v_readlane_b32 s82, v37, 23
	v_readlane_b32 s83, v38, 23
	v_readlane_b32 s84, v39, 23
	v_readlane_b32 s85, v40, 23
	v_readlane_b32 s86, v41, 23
	s_waitcnt vmcnt(56)
; __device__ __forceinline__ void prep_phase(const Params& p, LAS unsigned char* lds) {
;     ...
;         for (int hh = 0; hh < 2; ++hh) {
; #pragma unroll 8
;             for (int kk = 0; kk < 64; ++kk) {
;                 const float wv = wp[(size_t)(hh * 64 + kk) * 6144];
; #pragma unroll
;                 for (int b = 0; b < 9; ++b) ac[b] += __int_as_float(__builtin_amdgcn_readlane(__float_as_int(sv[b][hh]), kk)) * wv;
	v_pk_fma_f32 v[12:13], v[114:115], s[18:19], v[12:13] op_sel_hi:[0,1,1]
	v_pk_fma_f32 v[10:11], v[114:115], s[20:21], v[10:11] op_sel_hi:[0,1,1]
	v_pk_fma_f32 v[8:9], v[114:115], s[22:23], v[8:9] op_sel_hi:[0,1,1]
	v_pk_fma_f32 v[6:7], v[114:115], s[24:25], v[6:7] op_sel_hi:[0,1,1]
	v_fmac_f32_e32 v2, s54, v114
	v_pk_fma_f32 v[12:13], v[116:117], s[0:1], v[12:13] op_sel_hi:[0,1,1]
	v_pk_fma_f32 v[10:11], v[116:117], s[26:27], v[10:11] op_sel_hi:[0,1,1]
	v_pk_fma_f32 v[8:9], v[116:117], s[28:29], v[8:9] op_sel_hi:[0,1,1]
	v_pk_fma_f32 v[6:7], v[116:117], s[30:31], v[6:7] op_sel_hi:[0,1,1]
	v_fmac_f32_e32 v2, s87, v116
	v_pk_fma_f32 v[12:13], v[118:119], s[34:35], v[12:13] op_sel_hi:[0,1,1]
	v_pk_fma_f32 v[10:11], v[118:119], s[36:37], v[10:11] op_sel_hi:[0,1,1]
	v_pk_fma_f32 v[8:9], v[118:119], s[38:39], v[8:9] op_sel_hi:[0,1,1]
	v_pk_fma_f32 v[6:7], v[118:119], s[40:41], v[6:7] op_sel_hi:[0,1,1]
	v_fmac_f32_e32 v2, s88, v118
	v_pk_fma_f32 v[12:13], v[120:121], s[42:43], v[12:13] op_sel_hi:[0,1,1]
	v_pk_fma_f32 v[10:11], v[120:121], s[44:45], v[10:11] op_sel_hi:[0,1,1]
	v_pk_fma_f32 v[8:9], v[120:121], s[46:47], v[8:9] op_sel_hi:[0,1,1]
	v_pk_fma_f32 v[6:7], v[120:121], s[48:49], v[6:7] op_sel_hi:[0,1,1]
	v_fmac_f32_e32 v2, s55, v120
	v_pk_fma_f32 v[12:13], v[122:123], s[58:59], v[12:13] op_sel_hi:[0,1,1]
	v_pk_fma_f32 v[10:11], v[122:123], s[60:61], v[10:11] op_sel_hi:[0,1,1]
	v_pk_fma_f32 v[8:9], v[122:123], s[62:63], v[8:9] op_sel_hi:[0,1,1]
	v_pk_fma_f32 v[6:7], v[122:123], s[64:65], v[6:7] op_sel_hi:[0,1,1]
	v_fmac_f32_e32 v2, s89, v122
	v_pk_fma_f32 v[12:13], v[124:125], s[56:57], v[12:13] op_sel_hi:[0,1,1]
	v_pk_fma_f32 v[10:11], v[124:125], s[66:67], v[10:11] op_sel_hi:[0,1,1]
	v_pk_fma_f32 v[8:9], v[124:125], s[68:69], v[8:9] op_sel_hi:[0,1,1]
	v_pk_fma_f32 v[6:7], v[124:125], s[70:71], v[6:7] op_sel_hi:[0,1,1]
	v_fmac_f32_e32 v2, s90, v124
	v_pk_fma_f32 v[12:13], v[126:127], s[12:13], v[12:13] op_sel_hi:[0,1,1]
	v_pk_fma_f32 v[10:11], v[126:127], s[72:73], v[10:11] op_sel_hi:[0,1,1]
	v_pk_fma_f32 v[8:9], v[126:127], s[74:75], v[8:9] op_sel_hi:[0,1,1]
	v_pk_fma_f32 v[6:7], v[126:127], s[76:77], v[6:7] op_sel_hi:[0,1,1]
	v_fmac_f32_e32 v2, s50, v126
	v_pk_fma_f32 v[12:13], v[128:129], s[78:79], v[12:13] op_sel_hi:[0,1,1]
	v_pk_fma_f32 v[10:11], v[128:129], s[80:81], v[10:11] op_sel_hi:[0,1,1]
	v_pk_fma_f32 v[8:9], v[128:129], s[82:83], v[8:9] op_sel_hi:[0,1,1]
	v_pk_fma_f32 v[6:7], v[128:129], s[84:85], v[6:7] op_sel_hi:[0,1,1]
	v_fmac_f32_e32 v2, s86, v128
	global_load_dword v114, v[246:247], off
	v_lshl_add_u64 v[246:247], v[246:247], 0, s[100:101]
	global_load_dword v116, v[246:247], off
	v_lshl_add_u64 v[246:247], v[246:247], 0, s[100:101]
	global_load_dword v118, v[246:247], off
	v_lshl_add_u64 v[246:247], v[246:247], 0, s[100:101]
	global_load_dword v120, v[246:247], off
	v_lshl_add_u64 v[246:247], v[246:247], 0, s[100:101]
	global_load_dword v122, v[246:247], off
	v_lshl_add_u64 v[246:247], v[246:247], 0, s[100:101]
	global_load_dword v124, v[246:247], off
	v_lshl_add_u64 v[246:247], v[246:247], 0, s[100:101]
	global_load_dword v126, v[246:247], off
	v_lshl_add_u64 v[246:247], v[246:247], 0, s[100:101]
	global_load_dword v128, v[246:247], off
	v_lshl_add_u64 v[246:247], v[246:247], 0, s[100:101]
	v_readlane_b32 s18, v33, 24
	v_readlane_b32 s19, v34, 24
	v_readlane_b32 s20, v35, 24
	v_readlane_b32 s21, v36, 24
	v_readlane_b32 s22, v37, 24
	v_readlane_b32 s23, v38, 24
	v_readlane_b32 s24, v39, 24
	v_readlane_b32 s25, v40, 24
	v_readlane_b32 s54, v41, 24
	v_readlane_b32 s0, v33, 25
	v_readlane_b32 s1, v34, 25
	v_readlane_b32 s26, v35, 25
	v_readlane_b32 s27, v36, 25
	v_readlane_b32 s28, v37, 25
	v_readlane_b32 s29, v38, 25
	v_readlane_b32 s30, v39, 25
	v_readlane_b32 s31, v40, 25
	v_readlane_b32 s87, v41, 25
	v_readlane_b32 s34, v33, 26
	v_readlane_b32 s35, v34, 26
	v_readlane_b32 s36, v35, 26
	v_readlane_b32 s37, v36, 26
	v_readlane_b32 s38, v37, 26
	v_readlane_b32 s39, v38, 26
	v_readlane_b32 s40, v39, 26
	v_readlane_b32 s41, v40, 26
	v_readlane_b32 s88, v41, 26
	v_readlane_b32 s42, v33, 27
	v_readlane_b32 s43, v34, 27
	v_readlane_b32 s44, v35, 27
	v_readlane_b32 s45, v36, 27
	v_readlane_b32 s46, v37, 27
	v_readlane_b32 s47, v38, 27
	v_readlane_b32 s48, v39, 27
	v_readlane_b32 s49, v40, 27
	v_readlane_b32 s55, v41, 27
	v_readlane_b32 s58, v33, 28
	v_readlane_b32 s59, v34, 28
	v_readlane_b32 s60, v35, 28
	v_readlane_b32 s61, v36, 28
	v_readlane_b32 s62, v37, 28
	v_readlane_b32 s63, v38, 28
	v_readlane_b32 s64, v39, 28
	v_readlane_b32 s65, v40, 28
	v_readlane_b32 s89, v41, 28
	v_readlane_b32 s56, v33, 29
	v_readlane_b32 s57, v34, 29
	v_readlane_b32 s66, v35, 29
	v_readlane_b32 s67, v36, 29
	v_readlane_b32 s68, v37, 29
	v_readlane_b32 s69, v38, 29
	v_readlane_b32 s70, v39, 29
	v_readlane_b32 s71, v40, 29
	v_readlane_b32 s90, v41, 29
	v_readlane_b32 s12, v33, 30
	v_readlane_b32 s13, v34, 30
	v_readlane_b32 s72, v35, 30
	v_readlane_b32 s73, v36, 30
	v_readlane_b32 s74, v37, 30
	v_readlane_b32 s75, v38, 30
	v_readlane_b32 s76, v39, 30
	v_readlane_b32 s77, v40, 30
	v_readlane_b32 s50, v41, 30
	v_readlane_b32 s78, v33, 31
	v_readlane_b32 s79, v34, 31
	v_readlane_b32 s80, v35, 31
	v_readlane_b32 s81, v36, 31
	v_readlane_b32 s82, v37, 31
	v_readlane_b32 s83, v38, 31
	v_readlane_b32 s84, v39, 31
	v_readlane_b32 s85, v40, 31
	v_readlane_b32 s86, v41, 31
	s_waitcnt vmcnt(56)
; __device__ __forceinline__ void prep_phase(const Params& p, LAS unsigned char* lds) {
;     ...
;         for (int hh = 0; hh < 2; ++hh) {
; #pragma unroll 8
;             for (int kk = 0; kk < 64; ++kk) {
;                 const float wv = wp[(size_t)(hh * 64 + kk) * 6144];
; #pragma unroll
;                 for (int b = 0; b < 9; ++b) ac[b] += __int_as_float(__builtin_amdgcn_readlane(__float_as_int(sv[b][hh]), kk)) * wv;
	v_pk_fma_f32 v[12:13], v[130:131], s[18:19], v[12:13] op_sel_hi:[0,1,1]
	v_pk_fma_f32 v[10:11], v[130:131], s[20:21], v[10:11] op_sel_hi:[0,1,1]
	v_pk_fma_f32 v[8:9], v[130:131], s[22:23], v[8:9] op_sel_hi:[0,1,1]
	v_pk_fma_f32 v[6:7], v[130:131], s[24:25], v[6:7] op_sel_hi:[0,1,1]
	v_fmac_f32_e32 v2, s54, v130
	v_pk_fma_f32 v[12:13], v[132:133], s[0:1], v[12:13] op_sel_hi:[0,1,1]
	v_pk_fma_f32 v[10:11], v[132:133], s[26:27], v[10:11] op_sel_hi:[0,1,1]
	v_pk_fma_f32 v[8:9], v[132:133], s[28:29], v[8:9] op_sel_hi:[0,1,1]
	v_pk_fma_f32 v[6:7], v[132:133], s[30:31], v[6:7] op_sel_hi:[0,1,1]
	v_fmac_f32_e32 v2, s87, v132
	v_pk_fma_f32 v[12:13], v[134:135], s[34:35], v[12:13] op_sel_hi:[0,1,1]
	v_pk_fma_f32 v[10:11], v[134:135], s[36:37], v[10:11] op_sel_hi:[0,1,1]
	v_pk_fma_f32 v[8:9], v[134:135], s[38:39], v[8:9] op_sel_hi:[0,1,1]
	v_pk_fma_f32 v[6:7], v[134:135], s[40:41], v[6:7] op_sel_hi:[0,1,1]
	v_fmac_f32_e32 v2, s88, v134
	v_pk_fma_f32 v[12:13], v[136:137], s[42:43], v[12:13] op_sel_hi:[0,1,1]
	v_pk_fma_f32 v[10:11], v[136:137], s[44:45], v[10:11] op_sel_hi:[0,1,1]
	v_pk_fma_f32 v[8:9], v[136:137], s[46:47], v[8:9] op_sel_hi:[0,1,1]
	v_pk_fma_f32 v[6:7], v[136:137], s[48:49], v[6:7] op_sel_hi:[0,1,1]
	v_fmac_f32_e32 v2, s55, v136
	v_pk_fma_f32 v[12:13], v[138:139], s[58:59], v[12:13] op_sel_hi:[0,1,1]
	v_pk_fma_f32 v[10:11], v[138:139], s[60:61], v[10:11] op_sel_hi:[0,1,1]
	v_pk_fma_f32 v[8:9], v[138:139], s[62:63], v[8:9] op_sel_hi:[0,1,1]
	v_pk_fma_f32 v[6:7], v[138:139], s[64:65], v[6:7] op_sel_hi:[0,1,1]
	v_fmac_f32_e32 v2, s89, v138
	v_pk_fma_f32 v[12:13], v[140:141], s[56:57], v[12:13] op_sel_hi:[0,1,1]
	v_pk_fma_f32 v[10:11], v[140:141], s[66:67], v[10:11] op_sel_hi:[0,1,1]
	v_pk_fma_f32 v[8:9], v[140:141], s[68:69], v[8:9] op_sel_hi:[0,1,1]
	v_pk_fma_f32 v[6:7], v[140:141], s[70:71], v[6:7] op_sel_hi:[0,1,1]
	v_fmac_f32_e32 v2, s90, v140
	v_pk_fma_f32 v[12:13], v[142:143], s[12:13], v[12:13] op_sel_hi:[0,1,1]
	v_pk_fma_f32 v[10:11], v[142:143], s[72:73], v[10:11] op_sel_hi:[0,1,1]
	v_pk_fma_f32 v[8:9], v[142:143], s[74:75], v[8:9] op_sel_hi:[0,1,1]
	v_pk_fma_f32 v[6:7], v[142:143], s[76:77], v[6:7] op_sel_hi:[0,1,1]
	v_fmac_f32_e32 v2, s50, v142
	v_pk_fma_f32 v[12:13], v[144:145], s[78:79], v[12:13] op_sel_hi:[0,1,1]
	v_pk_fma_f32 v[10:11], v[144:145], s[80:81], v[10:11] op_sel_hi:[0,1,1]
	v_pk_fma_f32 v[8:9], v[144:145], s[82:83], v[8:9] op_sel_hi:[0,1,1]
	v_pk_fma_f32 v[6:7], v[144:145], s[84:85], v[6:7] op_sel_hi:[0,1,1]
	v_fmac_f32_e32 v2, s86, v144
	global_load_dword v130, v[246:247], off
	v_lshl_add_u64 v[246:247], v[246:247], 0, s[100:101]
	global_load_dword v132, v[246:247], off
	v_lshl_add_u64 v[246:247], v[246:247], 0, s[100:101]
	global_load_dword v134, v[246:247], off
	v_lshl_add_u64 v[246:247], v[246:247], 0, s[100:101]
	global_load_dword v136, v[246:247], off
	v_lshl_add_u64 v[246:247], v[246:247], 0, s[100:101]
	global_load_dword v138, v[246:247], off
	v_lshl_add_u64 v[246:247], v[246:247], 0, s[100:101]
	global_load_dword v140, v[246:247], off
	v_lshl_add_u64 v[246:247], v[246:247], 0, s[100:101]
	global_load_dword v142, v[246:247], off
	v_lshl_add_u64 v[246:247], v[246:247], 0, s[100:101]
	global_load_dword v144, v[246:247], off
	v_lshl_add_u64 v[246:247], v[246:247], 0, s[100:101]
	v_readlane_b32 s18, v33, 32
	v_readlane_b32 s19, v34, 32
	v_readlane_b32 s20, v35, 32
	v_readlane_b32 s21, v36, 32
	v_readlane_b32 s22, v37, 32
	v_readlane_b32 s23, v38, 32
	v_readlane_b32 s24, v39, 32
	v_readlane_b32 s25, v40, 32
	v_readlane_b32 s54, v41, 32
	v_readlane_b32 s0, v33, 33
	v_readlane_b32 s1, v34, 33
	v_readlane_b32 s26, v35, 33
	v_readlane_b32 s27, v36, 33
	v_readlane_b32 s28, v37, 33
	v_readlane_b32 s29, v38, 33
	v_readlane_b32 s30, v39, 33
	v_readlane_b32 s31, v40, 33
	v_readlane_b32 s87, v41, 33
	v_readlane_b32 s34, v33, 34
	v_readlane_b32 s35, v34, 34
	v_readlane_b32 s36, v35, 34
	v_readlane_b32 s37, v36, 34
	v_readlane_b32 s38, v37, 34
	v_readlane_b32 s39, v38, 34
	v_readlane_b32 s40, v39, 34
	v_readlane_b32 s41, v40, 34
	v_readlane_b32 s88, v41, 34
	v_readlane_b32 s42, v33, 35
	v_readlane_b32 s43, v34, 35
	v_readlane_b32 s44, v35, 35
	v_readlane_b32 s45, v36, 35
	v_readlane_b32 s46, v37, 35
	v_readlane_b32 s47, v38, 35
	v_readlane_b32 s48, v39, 35
	v_readlane_b32 s49, v40, 35
	v_readlane_b32 s55, v41, 35
	v_readlane_b32 s58, v33, 36
	v_readlane_b32 s59, v34, 36
	v_readlane_b32 s60, v35, 36
	v_readlane_b32 s61, v36, 36
	v_readlane_b32 s62, v37, 36
	v_readlane_b32 s63, v38, 36
	v_readlane_b32 s64, v39, 36
	v_readlane_b32 s65, v40, 36
	v_readlane_b32 s89, v41, 36
	v_readlane_b32 s56, v33, 37
	v_readlane_b32 s57, v34, 37
	v_readlane_b32 s66, v35, 37
	v_readlane_b32 s67, v36, 37
	v_readlane_b32 s68, v37, 37
	v_readlane_b32 s69, v38, 37
	v_readlane_b32 s70, v39, 37
	v_readlane_b32 s71, v40, 37
	v_readlane_b32 s90, v41, 37
	v_readlane_b32 s12, v33, 38
	v_readlane_b32 s13, v34, 38
	v_readlane_b32 s72, v35, 38
	v_readlane_b32 s73, v36, 38
	v_readlane_b32 s74, v37, 38
	v_readlane_b32 s75, v38, 38
	v_readlane_b32 s76, v39, 38
	v_readlane_b32 s77, v40, 38
	v_readlane_b32 s50, v41, 38
	v_readlane_b32 s78, v33, 39
	v_readlane_b32 s79, v34, 39
	v_readlane_b32 s80, v35, 39
	v_readlane_b32 s81, v36, 39
	v_readlane_b32 s82, v37, 39
	v_readlane_b32 s83, v38, 39
	v_readlane_b32 s84, v39, 39
	v_readlane_b32 s85, v40, 39
	v_readlane_b32 s86, v41, 39
	s_waitcnt vmcnt(56)
; __device__ __forceinline__ void prep_phase(const Params& p, LAS unsigned char* lds) {
;     ...
;         for (int hh = 0; hh < 2; ++hh) {
; #pragma unroll 8
;             for (int kk = 0; kk < 64; ++kk) {
;                 const float wv = wp[(size_t)(hh * 64 + kk) * 6144];
; #pragma unroll
;                 for (int b = 0; b < 9; ++b) ac[b] += __int_as_float(__builtin_amdgcn_readlane(__float_as_int(sv[b][hh]), kk)) * wv;
	v_pk_fma_f32 v[12:13], v[146:147], s[18:19], v[12:13] op_sel_hi:[0,1,1]
	v_pk_fma_f32 v[10:11], v[146:147], s[20:21], v[10:11] op_sel_hi:[0,1,1]
	v_pk_fma_f32 v[8:9], v[146:147], s[22:23], v[8:9] op_sel_hi:[0,1,1]
	v_pk_fma_f32 v[6:7], v[146:147], s[24:25], v[6:7] op_sel_hi:[0,1,1]
	v_fmac_f32_e32 v2, s54, v146
	v_pk_fma_f32 v[12:13], v[148:149], s[0:1], v[12:13] op_sel_hi:[0,1,1]
	v_pk_fma_f32 v[10:11], v[148:149], s[26:27], v[10:11] op_sel_hi:[0,1,1]
	v_pk_fma_f32 v[8:9], v[148:149], s[28:29], v[8:9] op_sel_hi:[0,1,1]
	v_pk_fma_f32 v[6:7], v[148:149], s[30:31], v[6:7] op_sel_hi:[0,1,1]
	v_fmac_f32_e32 v2, s87, v148
	v_pk_fma_f32 v[12:13], v[150:151], s[34:35], v[12:13] op_sel_hi:[0,1,1]
	v_pk_fma_f32 v[10:11], v[150:151], s[36:37], v[10:11] op_sel_hi:[0,1,1]
	v_pk_fma_f32 v[8:9], v[150:151], s[38:39], v[8:9] op_sel_hi:[0,1,1]
	v_pk_fma_f32 v[6:7], v[150:151], s[40:41], v[6:7] op_sel_hi:[0,1,1]
	v_fmac_f32_e32 v2, s88, v150
	v_pk_fma_f32 v[12:13], v[152:153], s[42:43], v[12:13] op_sel_hi:[0,1,1]
	v_pk_fma_f32 v[10:11], v[152:153], s[44:45], v[10:11] op_sel_hi:[0,1,1]
	v_pk_fma_f32 v[8:9], v[152:153], s[46:47], v[8:9] op_sel_hi:[0,1,1]
	v_pk_fma_f32 v[6:7], v[152:153], s[48:49], v[6:7] op_sel_hi:[0,1,1]
	v_fmac_f32_e32 v2, s55, v152
	v_pk_fma_f32 v[12:13], v[154:155], s[58:59], v[12:13] op_sel_hi:[0,1,1]
	v_pk_fma_f32 v[10:11], v[154:155], s[60:61], v[10:11] op_sel_hi:[0,1,1]
	v_pk_fma_f32 v[8:9], v[154:155], s[62:63], v[8:9] op_sel_hi:[0,1,1]
	v_pk_fma_f32 v[6:7], v[154:155], s[64:65], v[6:7] op_sel_hi:[0,1,1]
	v_fmac_f32_e32 v2, s89, v154
	v_pk_fma_f32 v[12:13], v[158:159], s[56:57], v[12:13] op_sel_hi:[0,1,1]
	v_pk_fma_f32 v[10:11], v[158:159], s[66:67], v[10:11] op_sel_hi:[0,1,1]
	v_pk_fma_f32 v[8:9], v[158:159], s[68:69], v[8:9] op_sel_hi:[0,1,1]
	v_pk_fma_f32 v[6:7], v[158:159], s[70:71], v[6:7] op_sel_hi:[0,1,1]
	v_fmac_f32_e32 v2, s90, v158
	v_pk_fma_f32 v[12:13], v[160:161], s[12:13], v[12:13] op_sel_hi:[0,1,1]
	v_pk_fma_f32 v[10:11], v[160:161], s[72:73], v[10:11] op_sel_hi:[0,1,1]
	v_pk_fma_f32 v[8:9], v[160:161], s[74:75], v[8:9] op_sel_hi:[0,1,1]
	v_pk_fma_f32 v[6:7], v[160:161], s[76:77], v[6:7] op_sel_hi:[0,1,1]
	v_fmac_f32_e32 v2, s50, v160
	v_pk_fma_f32 v[12:13], v[162:163], s[78:79], v[12:13] op_sel_hi:[0,1,1]
	v_pk_fma_f32 v[10:11], v[162:163], s[80:81], v[10:11] op_sel_hi:[0,1,1]
	v_pk_fma_f32 v[8:9], v[162:163], s[82:83], v[8:9] op_sel_hi:[0,1,1]
	v_pk_fma_f32 v[6:7], v[162:163], s[84:85], v[6:7] op_sel_hi:[0,1,1]
	v_fmac_f32_e32 v2, s86, v162
	global_load_dword v146, v[246:247], off
	v_lshl_add_u64 v[246:247], v[246:247], 0, s[100:101]
	global_load_dword v148, v[246:247], off
	v_lshl_add_u64 v[246:247], v[246:247], 0, s[100:101]
	global_load_dword v150, v[246:247], off
	v_lshl_add_u64 v[246:247], v[246:247], 0, s[100:101]
	global_load_dword v152, v[246:247], off
	v_lshl_add_u64 v[246:247], v[246:247], 0, s[100:101]
	global_load_dword v154, v[246:247], off
	v_lshl_add_u64 v[246:247], v[246:247], 0, s[100:101]
	global_load_dword v158, v[246:247], off
	v_lshl_add_u64 v[246:247], v[246:247], 0, s[100:101]
	global_load_dword v160, v[246:247], off
	v_lshl_add_u64 v[246:247], v[246:247], 0, s[100:101]
	global_load_dword v162, v[246:247], off
	v_lshl_add_u64 v[246:247], v[246:247], 0, s[100:101]
	v_readlane_b32 s18, v33, 40
	v_readlane_b32 s19, v34, 40
	v_readlane_b32 s20, v35, 40
	v_readlane_b32 s21, v36, 40
	v_readlane_b32 s22, v37, 40
	v_readlane_b32 s23, v38, 40
	v_readlane_b32 s24, v39, 40
	v_readlane_b32 s25, v40, 40
	v_readlane_b32 s54, v41, 40
	v_readlane_b32 s0, v33, 41
	v_readlane_b32 s1, v34, 41
	v_readlane_b32 s26, v35, 41
	v_readlane_b32 s27, v36, 41
	v_readlane_b32 s28, v37, 41
	v_readlane_b32 s29, v38, 41
	v_readlane_b32 s30, v39, 41
	v_readlane_b32 s31, v40, 41
	v_readlane_b32 s87, v41, 41
	v_readlane_b32 s34, v33, 42
	v_readlane_b32 s35, v34, 42
	v_readlane_b32 s36, v35, 42
	v_readlane_b32 s37, v36, 42
	v_readlane_b32 s38, v37, 42
	v_readlane_b32 s39, v38, 42
	v_readlane_b32 s40, v39, 42
	v_readlane_b32 s41, v40, 42
	v_readlane_b32 s88, v41, 42
	v_readlane_b32 s42, v33, 43
	v_readlane_b32 s43, v34, 43
	v_readlane_b32 s44, v35, 43
	v_readlane_b32 s45, v36, 43
	v_readlane_b32 s46, v37, 43
	v_readlane_b32 s47, v38, 43
	v_readlane_b32 s48, v39, 43
	v_readlane_b32 s49, v40, 43
	v_readlane_b32 s55, v41, 43
	v_readlane_b32 s58, v33, 44
	v_readlane_b32 s59, v34, 44
	v_readlane_b32 s60, v35, 44
	v_readlane_b32 s61, v36, 44
	v_readlane_b32 s62, v37, 44
	v_readlane_b32 s63, v38, 44
	v_readlane_b32 s64, v39, 44
	v_readlane_b32 s65, v40, 44
	v_readlane_b32 s89, v41, 44
	v_readlane_b32 s56, v33, 45
	v_readlane_b32 s57, v34, 45
	v_readlane_b32 s66, v35, 45
	v_readlane_b32 s67, v36, 45
	v_readlane_b32 s68, v37, 45
	v_readlane_b32 s69, v38, 45
	v_readlane_b32 s70, v39, 45
	v_readlane_b32 s71, v40, 45
	v_readlane_b32 s90, v41, 45
	v_readlane_b32 s12, v33, 46
	v_readlane_b32 s13, v34, 46
	v_readlane_b32 s72, v35, 46
	v_readlane_b32 s73, v36, 46
	v_readlane_b32 s74, v37, 46
	v_readlane_b32 s75, v38, 46
	v_readlane_b32 s76, v39, 46
	v_readlane_b32 s77, v40, 46
	v_readlane_b32 s50, v41, 46
	v_readlane_b32 s78, v33, 47
	v_readlane_b32 s79, v34, 47
	v_readlane_b32 s80, v35, 47
	v_readlane_b32 s81, v36, 47
	v_readlane_b32 s82, v37, 47
	v_readlane_b32 s83, v38, 47
	v_readlane_b32 s84, v39, 47
	v_readlane_b32 s85, v40, 47
	v_readlane_b32 s86, v41, 47
	s_waitcnt vmcnt(56)
; __device__ __forceinline__ void prep_phase(const Params& p, LAS unsigned char* lds) {
;     ...
;         for (int hh = 0; hh < 2; ++hh) {
; #pragma unroll 8
;             for (int kk = 0; kk < 64; ++kk) {
;                 const float wv = wp[(size_t)(hh * 64 + kk) * 6144];
; #pragma unroll
;                 for (int b = 0; b < 9; ++b) ac[b] += __int_as_float(__builtin_amdgcn_readlane(__float_as_int(sv[b][hh]), kk)) * wv;
	v_pk_fma_f32 v[12:13], v[164:165], s[18:19], v[12:13] op_sel_hi:[0,1,1]
	v_pk_fma_f32 v[10:11], v[164:165], s[20:21], v[10:11] op_sel_hi:[0,1,1]
	v_pk_fma_f32 v[8:9], v[164:165], s[22:23], v[8:9] op_sel_hi:[0,1,1]
	v_pk_fma_f32 v[6:7], v[164:165], s[24:25], v[6:7] op_sel_hi:[0,1,1]
	v_fmac_f32_e32 v2, s54, v164
	v_pk_fma_f32 v[12:13], v[166:167], s[0:1], v[12:13] op_sel_hi:[0,1,1]
	v_pk_fma_f32 v[10:11], v[166:167], s[26:27], v[10:11] op_sel_hi:[0,1,1]
	v_pk_fma_f32 v[8:9], v[166:167], s[28:29], v[8:9] op_sel_hi:[0,1,1]
	v_pk_fma_f32 v[6:7], v[166:167], s[30:31], v[6:7] op_sel_hi:[0,1,1]
	v_fmac_f32_e32 v2, s87, v166
	v_pk_fma_f32 v[12:13], v[168:169], s[34:35], v[12:13] op_sel_hi:[0,1,1]
	v_pk_fma_f32 v[10:11], v[168:169], s[36:37], v[10:11] op_sel_hi:[0,1,1]
	v_pk_fma_f32 v[8:9], v[168:169], s[38:39], v[8:9] op_sel_hi:[0,1,1]
	v_pk_fma_f32 v[6:7], v[168:169], s[40:41], v[6:7] op_sel_hi:[0,1,1]
	v_fmac_f32_e32 v2, s88, v168
	v_pk_fma_f32 v[12:13], v[170:171], s[42:43], v[12:13] op_sel_hi:[0,1,1]
	v_pk_fma_f32 v[10:11], v[170:171], s[44:45], v[10:11] op_sel_hi:[0,1,1]
	v_pk_fma_f32 v[8:9], v[170:171], s[46:47], v[8:9] op_sel_hi:[0,1,1]
	v_pk_fma_f32 v[6:7], v[170:171], s[48:49], v[6:7] op_sel_hi:[0,1,1]
	v_fmac_f32_e32 v2, s55, v170
	v_pk_fma_f32 v[12:13], v[172:173], s[58:59], v[12:13] op_sel_hi:[0,1,1]
	v_pk_fma_f32 v[10:11], v[172:173], s[60:61], v[10:11] op_sel_hi:[0,1,1]
	v_pk_fma_f32 v[8:9], v[172:173], s[62:63], v[8:9] op_sel_hi:[0,1,1]
	v_pk_fma_f32 v[6:7], v[172:173], s[64:65], v[6:7] op_sel_hi:[0,1,1]
	v_fmac_f32_e32 v2, s89, v172
	v_pk_fma_f32 v[12:13], v[174:175], s[56:57], v[12:13] op_sel_hi:[0,1,1]
	v_pk_fma_f32 v[10:11], v[174:175], s[66:67], v[10:11] op_sel_hi:[0,1,1]
	v_pk_fma_f32 v[8:9], v[174:175], s[68:69], v[8:9] op_sel_hi:[0,1,1]
	v_pk_fma_f32 v[6:7], v[174:175], s[70:71], v[6:7] op_sel_hi:[0,1,1]
	v_fmac_f32_e32 v2, s90, v174
	v_pk_fma_f32 v[12:13], v[176:177], s[12:13], v[12:13] op_sel_hi:[0,1,1]
	v_pk_fma_f32 v[10:11], v[176:177], s[72:73], v[10:11] op_sel_hi:[0,1,1]
	v_pk_fma_f32 v[8:9], v[176:177], s[74:75], v[8:9] op_sel_hi:[0,1,1]
	v_pk_fma_f32 v[6:7], v[176:177], s[76:77], v[6:7] op_sel_hi:[0,1,1]
	v_fmac_f32_e32 v2, s50, v176
	v_pk_fma_f32 v[12:13], v[178:179], s[78:79], v[12:13] op_sel_hi:[0,1,1]
	v_pk_fma_f32 v[10:11], v[178:179], s[80:81], v[10:11] op_sel_hi:[0,1,1]
	v_pk_fma_f32 v[8:9], v[178:179], s[82:83], v[8:9] op_sel_hi:[0,1,1]
	v_pk_fma_f32 v[6:7], v[178:179], s[84:85], v[6:7] op_sel_hi:[0,1,1]
	v_fmac_f32_e32 v2, s86, v178
	global_load_dword v164, v[246:247], off
	v_lshl_add_u64 v[246:247], v[246:247], 0, s[100:101]
	global_load_dword v166, v[246:247], off
	v_lshl_add_u64 v[246:247], v[246:247], 0, s[100:101]
	global_load_dword v168, v[246:247], off
	v_lshl_add_u64 v[246:247], v[246:247], 0, s[100:101]
	global_load_dword v170, v[246:247], off
	v_lshl_add_u64 v[246:247], v[246:247], 0, s[100:101]
	global_load_dword v172, v[246:247], off
	v_lshl_add_u64 v[246:247], v[246:247], 0, s[100:101]
	global_load_dword v174, v[246:247], off
	v_lshl_add_u64 v[246:247], v[246:247], 0, s[100:101]
	global_load_dword v176, v[246:247], off
	v_lshl_add_u64 v[246:247], v[246:247], 0, s[100:101]
	global_load_dword v178, v[246:247], off
	v_lshl_add_u64 v[246:247], v[246:247], 0, s[100:101]
	v_readlane_b32 s18, v33, 48
	v_readlane_b32 s19, v34, 48
	v_readlane_b32 s20, v35, 48
	v_readlane_b32 s21, v36, 48
	v_readlane_b32 s22, v37, 48
	v_readlane_b32 s23, v38, 48
	v_readlane_b32 s24, v39, 48
	v_readlane_b32 s25, v40, 48
	v_readlane_b32 s54, v41, 48
	v_readlane_b32 s0, v33, 49
	v_readlane_b32 s1, v34, 49
	v_readlane_b32 s26, v35, 49
	v_readlane_b32 s27, v36, 49
	v_readlane_b32 s28, v37, 49
	v_readlane_b32 s29, v38, 49
	v_readlane_b32 s30, v39, 49
	v_readlane_b32 s31, v40, 49
	v_readlane_b32 s87, v41, 49
	v_readlane_b32 s34, v33, 50
	v_readlane_b32 s35, v34, 50
	v_readlane_b32 s36, v35, 50
	v_readlane_b32 s37, v36, 50
	v_readlane_b32 s38, v37, 50
	v_readlane_b32 s39, v38, 50
	v_readlane_b32 s40, v39, 50
	v_readlane_b32 s41, v40, 50
	v_readlane_b32 s88, v41, 50
	v_readlane_b32 s42, v33, 51
	v_readlane_b32 s43, v34, 51
	v_readlane_b32 s44, v35, 51
	v_readlane_b32 s45, v36, 51
	v_readlane_b32 s46, v37, 51
	v_readlane_b32 s47, v38, 51
	v_readlane_b32 s48, v39, 51
	v_readlane_b32 s49, v40, 51
	v_readlane_b32 s55, v41, 51
	v_readlane_b32 s58, v33, 52
	v_readlane_b32 s59, v34, 52
	v_readlane_b32 s60, v35, 52
	v_readlane_b32 s61, v36, 52
	v_readlane_b32 s62, v37, 52
	v_readlane_b32 s63, v38, 52
	v_readlane_b32 s64, v39, 52
	v_readlane_b32 s65, v40, 52
	v_readlane_b32 s89, v41, 52
	v_readlane_b32 s56, v33, 53
	v_readlane_b32 s57, v34, 53
	v_readlane_b32 s66, v35, 53
	v_readlane_b32 s67, v36, 53
	v_readlane_b32 s68, v37, 53
	v_readlane_b32 s69, v38, 53
	v_readlane_b32 s70, v39, 53
	v_readlane_b32 s71, v40, 53
	v_readlane_b32 s90, v41, 53
	v_readlane_b32 s12, v33, 54
	v_readlane_b32 s13, v34, 54
	v_readlane_b32 s72, v35, 54
	v_readlane_b32 s73, v36, 54
	v_readlane_b32 s74, v37, 54
	v_readlane_b32 s75, v38, 54
	v_readlane_b32 s76, v39, 54
	v_readlane_b32 s77, v40, 54
	v_readlane_b32 s50, v41, 54
	v_readlane_b32 s78, v33, 55
	v_readlane_b32 s79, v34, 55
	v_readlane_b32 s80, v35, 55
	v_readlane_b32 s81, v36, 55
	v_readlane_b32 s82, v37, 55
	v_readlane_b32 s83, v38, 55
	v_readlane_b32 s84, v39, 55
	v_readlane_b32 s85, v40, 55
	v_readlane_b32 s86, v41, 55
	s_waitcnt vmcnt(56)
; __device__ __forceinline__ void prep_phase(const Params& p, LAS unsigned char* lds) {
;     ...
;         for (int hh = 0; hh < 2; ++hh) {
; #pragma unroll 8
;             for (int kk = 0; kk < 64; ++kk) {
;                 const float wv = wp[(size_t)(hh * 64 + kk) * 6144];
; #pragma unroll
;                 for (int b = 0; b < 9; ++b) ac[b] += __int_as_float(__builtin_amdgcn_readlane(__float_as_int(sv[b][hh]), kk)) * wv;
	v_pk_fma_f32 v[12:13], v[180:181], s[18:19], v[12:13] op_sel_hi:[0,1,1]
	v_pk_fma_f32 v[10:11], v[180:181], s[20:21], v[10:11] op_sel_hi:[0,1,1]
	v_pk_fma_f32 v[8:9], v[180:181], s[22:23], v[8:9] op_sel_hi:[0,1,1]
	v_pk_fma_f32 v[6:7], v[180:181], s[24:25], v[6:7] op_sel_hi:[0,1,1]
	v_fmac_f32_e32 v2, s54, v180
	v_pk_fma_f32 v[12:13], v[182:183], s[0:1], v[12:13] op_sel_hi:[0,1,1]
	v_pk_fma_f32 v[10:11], v[182:183], s[26:27], v[10:11] op_sel_hi:[0,1,1]
	v_pk_fma_f32 v[8:9], v[182:183], s[28:29], v[8:9] op_sel_hi:[0,1,1]
	v_pk_fma_f32 v[6:7], v[182:183], s[30:31], v[6:7] op_sel_hi:[0,1,1]
	v_fmac_f32_e32 v2, s87, v182
	v_pk_fma_f32 v[12:13], v[184:185], s[34:35], v[12:13] op_sel_hi:[0,1,1]
	v_pk_fma_f32 v[10:11], v[184:185], s[36:37], v[10:11] op_sel_hi:[0,1,1]
	v_pk_fma_f32 v[8:9], v[184:185], s[38:39], v[8:9] op_sel_hi:[0,1,1]
	v_pk_fma_f32 v[6:7], v[184:185], s[40:41], v[6:7] op_sel_hi:[0,1,1]
	v_fmac_f32_e32 v2, s88, v184
	v_pk_fma_f32 v[12:13], v[186:187], s[42:43], v[12:13] op_sel_hi:[0,1,1]
	v_pk_fma_f32 v[10:11], v[186:187], s[44:45], v[10:11] op_sel_hi:[0,1,1]
	v_pk_fma_f32 v[8:9], v[186:187], s[46:47], v[8:9] op_sel_hi:[0,1,1]
	v_pk_fma_f32 v[6:7], v[186:187], s[48:49], v[6:7] op_sel_hi:[0,1,1]
	v_fmac_f32_e32 v2, s55, v186
	v_pk_fma_f32 v[12:13], v[188:189], s[58:59], v[12:13] op_sel_hi:[0,1,1]
	v_pk_fma_f32 v[10:11], v[188:189], s[60:61], v[10:11] op_sel_hi:[0,1,1]
	v_pk_fma_f32 v[8:9], v[188:189], s[62:63], v[8:9] op_sel_hi:[0,1,1]
	v_pk_fma_f32 v[6:7], v[188:189], s[64:65], v[6:7] op_sel_hi:[0,1,1]
	v_fmac_f32_e32 v2, s89, v188
	v_pk_fma_f32 v[12:13], v[190:191], s[56:57], v[12:13] op_sel_hi:[0,1,1]
	v_pk_fma_f32 v[10:11], v[190:191], s[66:67], v[10:11] op_sel_hi:[0,1,1]
	v_pk_fma_f32 v[8:9], v[190:191], s[68:69], v[8:9] op_sel_hi:[0,1,1]
	v_pk_fma_f32 v[6:7], v[190:191], s[70:71], v[6:7] op_sel_hi:[0,1,1]
	v_fmac_f32_e32 v2, s90, v190
	v_pk_fma_f32 v[12:13], v[194:195], s[12:13], v[12:13] op_sel_hi:[0,1,1]
	v_pk_fma_f32 v[10:11], v[194:195], s[72:73], v[10:11] op_sel_hi:[0,1,1]
	v_pk_fma_f32 v[8:9], v[194:195], s[74:75], v[8:9] op_sel_hi:[0,1,1]
	v_pk_fma_f32 v[6:7], v[194:195], s[76:77], v[6:7] op_sel_hi:[0,1,1]
	v_fmac_f32_e32 v2, s50, v194
	v_pk_fma_f32 v[12:13], v[196:197], s[78:79], v[12:13] op_sel_hi:[0,1,1]
	v_pk_fma_f32 v[10:11], v[196:197], s[80:81], v[10:11] op_sel_hi:[0,1,1]
	v_pk_fma_f32 v[8:9], v[196:197], s[82:83], v[8:9] op_sel_hi:[0,1,1]
	v_pk_fma_f32 v[6:7], v[196:197], s[84:85], v[6:7] op_sel_hi:[0,1,1]
	v_fmac_f32_e32 v2, s86, v196
	global_load_dword v180, v[246:247], off
	v_lshl_add_u64 v[246:247], v[246:247], 0, s[100:101]
	global_load_dword v182, v[246:247], off
	v_lshl_add_u64 v[246:247], v[246:247], 0, s[100:101]
	global_load_dword v184, v[246:247], off
	v_lshl_add_u64 v[246:247], v[246:247], 0, s[100:101]
	global_load_dword v186, v[246:247], off
	v_lshl_add_u64 v[246:247], v[246:247], 0, s[100:101]
	global_load_dword v188, v[246:247], off
	v_lshl_add_u64 v[246:247], v[246:247], 0, s[100:101]
	global_load_dword v190, v[246:247], off
	v_lshl_add_u64 v[246:247], v[246:247], 0, s[100:101]
	global_load_dword v194, v[246:247], off
	v_lshl_add_u64 v[246:247], v[246:247], 0, s[100:101]
	global_load_dword v196, v[246:247], off
	v_lshl_add_u64 v[246:247], v[246:247], 0, s[100:101]
	v_readlane_b32 s18, v33, 56
	v_readlane_b32 s19, v34, 56
	v_readlane_b32 s20, v35, 56
	v_readlane_b32 s21, v36, 56
	v_readlane_b32 s22, v37, 56
	v_readlane_b32 s23, v38, 56
	v_readlane_b32 s24, v39, 56
	v_readlane_b32 s25, v40, 56
	v_readlane_b32 s54, v41, 56
	v_readlane_b32 s0, v33, 57
	v_readlane_b32 s1, v34, 57
	v_readlane_b32 s26, v35, 57
	v_readlane_b32 s27, v36, 57
	v_readlane_b32 s28, v37, 57
	v_readlane_b32 s29, v38, 57
	v_readlane_b32 s30, v39, 57
	v_readlane_b32 s31, v40, 57
	v_readlane_b32 s87, v41, 57
	v_readlane_b32 s34, v33, 58
	v_readlane_b32 s35, v34, 58
	v_readlane_b32 s36, v35, 58
	v_readlane_b32 s37, v36, 58
	v_readlane_b32 s38, v37, 58
	v_readlane_b32 s39, v38, 58
	v_readlane_b32 s40, v39, 58
	v_readlane_b32 s41, v40, 58
	v_readlane_b32 s88, v41, 58
	v_readlane_b32 s42, v33, 59
	v_readlane_b32 s43, v34, 59
	v_readlane_b32 s44, v35, 59
	v_readlane_b32 s45, v36, 59
	v_readlane_b32 s46, v37, 59
	v_readlane_b32 s47, v38, 59
	v_readlane_b32 s48, v39, 59
	v_readlane_b32 s49, v40, 59
	v_readlane_b32 s55, v41, 59
	v_readlane_b32 s58, v33, 60
	v_readlane_b32 s59, v34, 60
	v_readlane_b32 s60, v35, 60
	v_readlane_b32 s61, v36, 60
	v_readlane_b32 s62, v37, 60
	v_readlane_b32 s63, v38, 60
	v_readlane_b32 s64, v39, 60
	v_readlane_b32 s65, v40, 60
	v_readlane_b32 s89, v41, 60
	v_readlane_b32 s56, v33, 61
	v_readlane_b32 s57, v34, 61
	v_readlane_b32 s66, v35, 61
	v_readlane_b32 s67, v36, 61
	v_readlane_b32 s68, v37, 61
	v_readlane_b32 s69, v38, 61
	v_readlane_b32 s70, v39, 61
	v_readlane_b32 s71, v40, 61
	v_readlane_b32 s90, v41, 61
	v_readlane_b32 s12, v33, 62
	v_readlane_b32 s13, v34, 62
	v_readlane_b32 s72, v35, 62
	v_readlane_b32 s73, v36, 62
	v_readlane_b32 s74, v37, 62
	v_readlane_b32 s75, v38, 62
	v_readlane_b32 s76, v39, 62
	v_readlane_b32 s77, v40, 62
	v_readlane_b32 s50, v41, 62
	v_readlane_b32 s78, v33, 63
	v_readlane_b32 s79, v34, 63
	v_readlane_b32 s80, v35, 63
	v_readlane_b32 s81, v36, 63
	v_readlane_b32 s82, v37, 63
	v_readlane_b32 s83, v38, 63
	v_readlane_b32 s84, v39, 63
	v_readlane_b32 s85, v40, 63
	v_readlane_b32 s86, v41, 63
	s_waitcnt vmcnt(56)
; __device__ __forceinline__ float sigmoidf_(float v) { return __builtin_amdgcn_rcpf(1.f + __expf(-v)); }
; __device__ __forceinline__ void prep_phase(const Params& p, LAS unsigned char* lds) {
;     ...
;             for (int hh = 0; hh < 2; ++hh) { const int k = k0 + hh * 64 + lane; const float cv = (b < 8) ? p.c[b * DM + k] : p.c_ctx[k]; sv[b][hh] = cv * sigmoidf_(cv); }
;         float ac[9];
; #pragma unroll
;         for (int b = 0; b < 9; ++b) ac[b] = 0.f;
;         const float* wp = p.w_ada + ((size_t)l * DM + k0) * 6144 + col;
; #pragma unroll
;         for (int hh = 0; hh < 2; ++hh) {
; #pragma unroll 8
;             for (int kk = 0; kk < 64; ++kk) {
;                 const float wv = wp[(size_t)(hh * 64 + kk) * 6144];
; #pragma unroll
;                 for (int b = 0; b < 9; ++b) ac[b] += __int_as_float(__builtin_amdgcn_readlane(__float_as_int(sv[b][hh]), kk)) * wv;
	v_pk_fma_f32 v[12:13], v[198:199], s[18:19], v[12:13] op_sel_hi:[0,1,1]
	v_pk_fma_f32 v[10:11], v[198:199], s[20:21], v[10:11] op_sel_hi:[0,1,1]
	v_pk_fma_f32 v[8:9], v[198:199], s[22:23], v[8:9] op_sel_hi:[0,1,1]
	v_pk_fma_f32 v[6:7], v[198:199], s[24:25], v[6:7] op_sel_hi:[0,1,1]
	v_fmac_f32_e32 v2, s54, v198
	v_pk_fma_f32 v[12:13], v[202:203], s[0:1], v[12:13] op_sel_hi:[0,1,1]
	v_pk_fma_f32 v[10:11], v[202:203], s[26:27], v[10:11] op_sel_hi:[0,1,1]
	v_pk_fma_f32 v[8:9], v[202:203], s[28:29], v[8:9] op_sel_hi:[0,1,1]
	v_pk_fma_f32 v[6:7], v[202:203], s[30:31], v[6:7] op_sel_hi:[0,1,1]
	v_fmac_f32_e32 v2, s87, v202
	v_pk_fma_f32 v[12:13], v[204:205], s[34:35], v[12:13] op_sel_hi:[0,1,1]
	v_pk_fma_f32 v[10:11], v[204:205], s[36:37], v[10:11] op_sel_hi:[0,1,1]
	v_pk_fma_f32 v[8:9], v[204:205], s[38:39], v[8:9] op_sel_hi:[0,1,1]
	v_pk_fma_f32 v[6:7], v[204:205], s[40:41], v[6:7] op_sel_hi:[0,1,1]
	v_fmac_f32_e32 v2, s88, v204
	v_pk_fma_f32 v[12:13], v[206:207], s[42:43], v[12:13] op_sel_hi:[0,1,1]
	v_pk_fma_f32 v[10:11], v[206:207], s[44:45], v[10:11] op_sel_hi:[0,1,1]
	v_pk_fma_f32 v[8:9], v[206:207], s[46:47], v[8:9] op_sel_hi:[0,1,1]
	v_pk_fma_f32 v[6:7], v[206:207], s[48:49], v[6:7] op_sel_hi:[0,1,1]
	v_fmac_f32_e32 v2, s55, v206
	v_pk_fma_f32 v[12:13], v[208:209], s[58:59], v[12:13] op_sel_hi:[0,1,1]
	v_pk_fma_f32 v[10:11], v[208:209], s[60:61], v[10:11] op_sel_hi:[0,1,1]
	v_pk_fma_f32 v[8:9], v[208:209], s[62:63], v[8:9] op_sel_hi:[0,1,1]
	v_pk_fma_f32 v[6:7], v[208:209], s[64:65], v[6:7] op_sel_hi:[0,1,1]
	v_fmac_f32_e32 v2, s89, v208
	v_pk_fma_f32 v[12:13], v[210:211], s[56:57], v[12:13] op_sel_hi:[0,1,1]
	v_pk_fma_f32 v[10:11], v[210:211], s[66:67], v[10:11] op_sel_hi:[0,1,1]
	v_pk_fma_f32 v[8:9], v[210:211], s[68:69], v[8:9] op_sel_hi:[0,1,1]
	v_pk_fma_f32 v[6:7], v[210:211], s[70:71], v[6:7] op_sel_hi:[0,1,1]
	v_fmac_f32_e32 v2, s90, v210
	v_pk_fma_f32 v[12:13], v[212:213], s[12:13], v[12:13] op_sel_hi:[0,1,1]
	v_pk_fma_f32 v[10:11], v[212:213], s[72:73], v[10:11] op_sel_hi:[0,1,1]
	v_pk_fma_f32 v[8:9], v[212:213], s[74:75], v[8:9] op_sel_hi:[0,1,1]
	v_pk_fma_f32 v[6:7], v[212:213], s[76:77], v[6:7] op_sel_hi:[0,1,1]
	v_fmac_f32_e32 v2, s50, v212
	v_pk_fma_f32 v[12:13], v[214:215], s[78:79], v[12:13] op_sel_hi:[0,1,1]
	v_pk_fma_f32 v[10:11], v[214:215], s[80:81], v[10:11] op_sel_hi:[0,1,1]
	v_pk_fma_f32 v[8:9], v[214:215], s[82:83], v[8:9] op_sel_hi:[0,1,1]
	v_pk_fma_f32 v[6:7], v[214:215], s[84:85], v[6:7] op_sel_hi:[0,1,1]
	v_fmac_f32_e32 v2, s86, v214
	global_load_dword v198, v[246:247], off
	v_lshl_add_u64 v[246:247], v[246:247], 0, s[100:101]
	global_load_dword v202, v[246:247], off
	v_lshl_add_u64 v[246:247], v[246:247], 0, s[100:101]
	global_load_dword v204, v[246:247], off
	v_lshl_add_u64 v[246:247], v[246:247], 0, s[100:101]
	global_load_dword v206, v[246:247], off
	v_lshl_add_u64 v[246:247], v[246:247], 0, s[100:101]
	global_load_dword v208, v[246:247], off
	v_lshl_add_u64 v[246:247], v[246:247], 0, s[100:101]
	global_load_dword v210, v[246:247], off
	v_lshl_add_u64 v[246:247], v[246:247], 0, s[100:101]
	global_load_dword v212, v[246:247], off
	v_lshl_add_u64 v[246:247], v[246:247], 0, s[100:101]
	global_load_dword v214, v[246:247], off
	v_lshl_add_u64 v[246:247], v[246:247], 0, s[100:101]
	v_mul_f32_e32 v16, 0xbfb8aa3b, v29
	v_exp_f32_e32 v16, v16
	v_mul_f32_e32 v17, 0xbfb8aa3b, v31
	v_exp_f32_e32 v17, v17
	v_mul_f32_e32 v18, 0xbfb8aa3b, v26
	v_mul_f32_e32 v19, 0xbfb8aa3b, v30
	v_mul_f32_e32 v20, 0xbfb8aa3b, v24
	v_mul_f32_e32 v21, 0xbfb8aa3b, v32
	v_mul_f32_e32 v33, 0xbfb8aa3b, v23
	v_mul_f32_e32 v34, 0xbfb8aa3b, v27
	v_mul_f32_e32 v35, 0xbfb8aa3b, v25
	v_exp_f32_e32 v18, v18
	v_exp_f32_e32 v19, v19
	v_exp_f32_e32 v20, v20
	v_exp_f32_e32 v21, v21
	v_exp_f32_e32 v33, v33
	v_exp_f32_e32 v34, v34
	v_exp_f32_e32 v35, v35
	v_add_f32_e32 v16, 1.0, v16
	v_rcp_f32_e32 v16, v16
	v_add_f32_e32 v17, 1.0, v17
	v_rcp_f32_e32 v17, v17
	v_add_f32_e32 v18, 1.0, v18
	v_add_f32_e32 v19, 1.0, v19
	v_add_f32_e32 v20, 1.0, v20
	v_add_f32_e32 v21, 1.0, v21
	v_add_f32_e32 v33, 1.0, v33
	v_add_f32_e32 v34, 1.0, v34
	v_add_f32_e32 v35, 1.0, v35
	v_rcp_f32_e32 v18, v18
	v_rcp_f32_e32 v19, v19
	v_rcp_f32_e32 v20, v20
	v_rcp_f32_e32 v21, v21
	v_rcp_f32_e32 v33, v33
	v_rcp_f32_e32 v34, v34
	v_rcp_f32_e32 v35, v35
	v_mul_f32_e32 v29, v29, v16
	v_add_u32_e32 v16, v67, v28
	v_mul_f32_e32 v31, v31, v17
	v_ashrrev_i32_e32 v17, 31, v16
	v_lshl_add_u64 v[14:15], v[16:17], 2, v[14:15]
	v_mul_f32_e32 v26, v26, v18
	v_mul_f32_e32 v30, v30, v19
	v_mul_f32_e32 v24, v24, v20
	v_mul_f32_e32 v32, v32, v21
	v_mul_f32_e32 v23, v23, v33
	v_mul_f32_e32 v27, v27, v34
	v_mul_f32_e32 v25, v25, v35
	v_lshl_add_u64 v[14:15], s[10:11], 0, v[14:15]
	s_mov_b32 s53, 0
	v_readlane_b32 s18, v29, 0
	v_readlane_b32 s19, v31, 0
	v_readlane_b32 s20, v26, 0
	v_readlane_b32 s21, v30, 0
	v_readlane_b32 s22, v24, 0
	v_readlane_b32 s23, v32, 0
	v_readlane_b32 s24, v23, 0
	v_readlane_b32 s25, v27, 0
	v_readlane_b32 s54, v25, 0
	v_readlane_b32 s0, v29, 1
	v_readlane_b32 s1, v31, 1
	v_readlane_b32 s26, v26, 1
	v_readlane_b32 s27, v30, 1
	v_readlane_b32 s28, v24, 1
	v_readlane_b32 s29, v32, 1
	v_readlane_b32 s30, v23, 1
	v_readlane_b32 s31, v27, 1
	v_readlane_b32 s87, v25, 1
	v_readlane_b32 s34, v29, 2
	v_readlane_b32 s35, v31, 2
	v_readlane_b32 s36, v26, 2
	v_readlane_b32 s37, v30, 2
	v_readlane_b32 s38, v24, 2
	v_readlane_b32 s39, v32, 2
	v_readlane_b32 s40, v23, 2
	v_readlane_b32 s41, v27, 2
	v_readlane_b32 s88, v25, 2
	v_readlane_b32 s42, v29, 3
	v_readlane_b32 s43, v31, 3
	v_readlane_b32 s44, v26, 3
	v_readlane_b32 s45, v30, 3
	v_readlane_b32 s46, v24, 3
	v_readlane_b32 s47, v32, 3
	v_readlane_b32 s48, v23, 3
	v_readlane_b32 s49, v27, 3
	v_readlane_b32 s55, v25, 3
	v_readlane_b32 s58, v29, 4
	v_readlane_b32 s59, v31, 4
	v_readlane_b32 s60, v26, 4
	v_readlane_b32 s61, v30, 4
	v_readlane_b32 s62, v24, 4
	v_readlane_b32 s63, v32, 4
	v_readlane_b32 s64, v23, 4
	v_readlane_b32 s65, v27, 4
	v_readlane_b32 s89, v25, 4
	v_readlane_b32 s56, v29, 5
	v_readlane_b32 s57, v31, 5
	v_readlane_b32 s66, v26, 5
	v_readlane_b32 s67, v30, 5
	v_readlane_b32 s68, v24, 5
	v_readlane_b32 s69, v32, 5
	v_readlane_b32 s70, v23, 5
	v_readlane_b32 s71, v27, 5
	v_readlane_b32 s90, v25, 5
	v_readlane_b32 s12, v29, 6
	v_readlane_b32 s13, v31, 6
	v_readlane_b32 s72, v26, 6
	v_readlane_b32 s73, v30, 6
	v_readlane_b32 s74, v24, 6
	v_readlane_b32 s75, v32, 6
	v_readlane_b32 s76, v23, 6
	v_readlane_b32 s77, v27, 6
	v_readlane_b32 s50, v25, 6
	v_readlane_b32 s78, v29, 7
	v_readlane_b32 s79, v31, 7
	v_readlane_b32 s80, v26, 7
	v_readlane_b32 s81, v30, 7
	v_readlane_b32 s82, v24, 7
	v_readlane_b32 s83, v32, 7
	v_readlane_b32 s84, v23, 7
	v_readlane_b32 s85, v27, 7
	v_readlane_b32 s86, v25, 7
	s_waitcnt vmcnt(56)
; __device__ __forceinline__ void prep_phase(const Params& p, LAS unsigned char* lds) {
;     ...
;         for (int hh = 0; hh < 2; ++hh) {
; #pragma unroll 8
;             for (int kk = 0; kk < 64; ++kk) {
;                 const float wv = wp[(size_t)(hh * 64 + kk) * 6144];
; #pragma unroll
;                 for (int b = 0; b < 9; ++b) ac[b] += __int_as_float(__builtin_amdgcn_readlane(__float_as_int(sv[b][hh]), kk)) * wv;
	v_pk_fma_f32 v[12:13], v[82:83], s[18:19], v[12:13] op_sel_hi:[0,1,1]
	v_pk_fma_f32 v[10:11], v[82:83], s[20:21], v[10:11] op_sel_hi:[0,1,1]
	v_pk_fma_f32 v[8:9], v[82:83], s[22:23], v[8:9] op_sel_hi:[0,1,1]
	v_pk_fma_f32 v[6:7], v[82:83], s[24:25], v[6:7] op_sel_hi:[0,1,1]
	v_fmac_f32_e32 v2, s54, v82
	v_pk_fma_f32 v[12:13], v[84:85], s[0:1], v[12:13] op_sel_hi:[0,1,1]
	v_pk_fma_f32 v[10:11], v[84:85], s[26:27], v[10:11] op_sel_hi:[0,1,1]
	v_pk_fma_f32 v[8:9], v[84:85], s[28:29], v[8:9] op_sel_hi:[0,1,1]
	v_pk_fma_f32 v[6:7], v[84:85], s[30:31], v[6:7] op_sel_hi:[0,1,1]
	v_fmac_f32_e32 v2, s87, v84
	v_pk_fma_f32 v[12:13], v[86:87], s[34:35], v[12:13] op_sel_hi:[0,1,1]
	v_pk_fma_f32 v[10:11], v[86:87], s[36:37], v[10:11] op_sel_hi:[0,1,1]
	v_pk_fma_f32 v[8:9], v[86:87], s[38:39], v[8:9] op_sel_hi:[0,1,1]
	v_pk_fma_f32 v[6:7], v[86:87], s[40:41], v[6:7] op_sel_hi:[0,1,1]
	v_fmac_f32_e32 v2, s88, v86
	v_pk_fma_f32 v[12:13], v[88:89], s[42:43], v[12:13] op_sel_hi:[0,1,1]
	v_pk_fma_f32 v[10:11], v[88:89], s[44:45], v[10:11] op_sel_hi:[0,1,1]
	v_pk_fma_f32 v[8:9], v[88:89], s[46:47], v[8:9] op_sel_hi:[0,1,1]
	v_pk_fma_f32 v[6:7], v[88:89], s[48:49], v[6:7] op_sel_hi:[0,1,1]
	v_fmac_f32_e32 v2, s55, v88
	v_pk_fma_f32 v[12:13], v[90:91], s[58:59], v[12:13] op_sel_hi:[0,1,1]
	v_pk_fma_f32 v[10:11], v[90:91], s[60:61], v[10:11] op_sel_hi:[0,1,1]
	v_pk_fma_f32 v[8:9], v[90:91], s[62:63], v[8:9] op_sel_hi:[0,1,1]
	v_pk_fma_f32 v[6:7], v[90:91], s[64:65], v[6:7] op_sel_hi:[0,1,1]
	v_fmac_f32_e32 v2, s89, v90
	v_pk_fma_f32 v[12:13], v[92:93], s[56:57], v[12:13] op_sel_hi:[0,1,1]
	v_pk_fma_f32 v[10:11], v[92:93], s[66:67], v[10:11] op_sel_hi:[0,1,1]
	v_pk_fma_f32 v[8:9], v[92:93], s[68:69], v[8:9] op_sel_hi:[0,1,1]
	v_pk_fma_f32 v[6:7], v[92:93], s[70:71], v[6:7] op_sel_hi:[0,1,1]
	v_fmac_f32_e32 v2, s90, v92
	v_pk_fma_f32 v[12:13], v[94:95], s[12:13], v[12:13] op_sel_hi:[0,1,1]
	v_pk_fma_f32 v[10:11], v[94:95], s[72:73], v[10:11] op_sel_hi:[0,1,1]
	v_pk_fma_f32 v[8:9], v[94:95], s[74:75], v[8:9] op_sel_hi:[0,1,1]
	v_pk_fma_f32 v[6:7], v[94:95], s[76:77], v[6:7] op_sel_hi:[0,1,1]
	v_fmac_f32_e32 v2, s50, v94
	v_pk_fma_f32 v[12:13], v[96:97], s[78:79], v[12:13] op_sel_hi:[0,1,1]
	v_pk_fma_f32 v[10:11], v[96:97], s[80:81], v[10:11] op_sel_hi:[0,1,1]
	v_pk_fma_f32 v[8:9], v[96:97], s[82:83], v[8:9] op_sel_hi:[0,1,1]
	v_pk_fma_f32 v[6:7], v[96:97], s[84:85], v[6:7] op_sel_hi:[0,1,1]
	v_fmac_f32_e32 v2, s86, v96
	v_readlane_b32 s18, v29, 8
	v_readlane_b32 s19, v31, 8
	v_readlane_b32 s20, v26, 8
	v_readlane_b32 s21, v30, 8
	v_readlane_b32 s22, v24, 8
	v_readlane_b32 s23, v32, 8
	v_readlane_b32 s24, v23, 8
	v_readlane_b32 s25, v27, 8
	v_readlane_b32 s54, v25, 8
	v_readlane_b32 s0, v29, 9
	v_readlane_b32 s1, v31, 9
	v_readlane_b32 s26, v26, 9
	v_readlane_b32 s27, v30, 9
	v_readlane_b32 s28, v24, 9
	v_readlane_b32 s29, v32, 9
	v_readlane_b32 s30, v23, 9
	v_readlane_b32 s31, v27, 9
	v_readlane_b32 s87, v25, 9
	v_readlane_b32 s34, v29, 10
	v_readlane_b32 s35, v31, 10
	v_readlane_b32 s36, v26, 10
	v_readlane_b32 s37, v30, 10
	v_readlane_b32 s38, v24, 10
	v_readlane_b32 s39, v32, 10
	v_readlane_b32 s40, v23, 10
	v_readlane_b32 s41, v27, 10
	v_readlane_b32 s88, v25, 10
	v_readlane_b32 s42, v29, 11
	v_readlane_b32 s43, v31, 11
	v_readlane_b32 s44, v26, 11
	v_readlane_b32 s45, v30, 11
	v_readlane_b32 s46, v24, 11
	v_readlane_b32 s47, v32, 11
	v_readlane_b32 s48, v23, 11
	v_readlane_b32 s49, v27, 11
	v_readlane_b32 s55, v25, 11
	v_readlane_b32 s58, v29, 12
	v_readlane_b32 s59, v31, 12
	v_readlane_b32 s60, v26, 12
	v_readlane_b32 s61, v30, 12
	v_readlane_b32 s62, v24, 12
	v_readlane_b32 s63, v32, 12
	v_readlane_b32 s64, v23, 12
	v_readlane_b32 s65, v27, 12
	v_readlane_b32 s89, v25, 12
	v_readlane_b32 s56, v29, 13
	v_readlane_b32 s57, v31, 13
	v_readlane_b32 s66, v26, 13
	v_readlane_b32 s67, v30, 13
	v_readlane_b32 s68, v24, 13
	v_readlane_b32 s69, v32, 13
	v_readlane_b32 s70, v23, 13
	v_readlane_b32 s71, v27, 13
	v_readlane_b32 s90, v25, 13
	v_readlane_b32 s12, v29, 14
	v_readlane_b32 s13, v31, 14
	v_readlane_b32 s72, v26, 14
	v_readlane_b32 s73, v30, 14
	v_readlane_b32 s74, v24, 14
	v_readlane_b32 s75, v32, 14
	v_readlane_b32 s76, v23, 14
	v_readlane_b32 s77, v27, 14
	v_readlane_b32 s50, v25, 14
	v_readlane_b32 s78, v29, 15
	v_readlane_b32 s79, v31, 15
	v_readlane_b32 s80, v26, 15
	v_readlane_b32 s81, v30, 15
	v_readlane_b32 s82, v24, 15
	v_readlane_b32 s83, v32, 15
	v_readlane_b32 s84, v23, 15
	v_readlane_b32 s85, v27, 15
	v_readlane_b32 s86, v25, 15
	s_waitcnt vmcnt(48)
; __device__ __forceinline__ void prep_phase(const Params& p, LAS unsigned char* lds) {
;     ...
;         for (int hh = 0; hh < 2; ++hh) {
; #pragma unroll 8
;             for (int kk = 0; kk < 64; ++kk) {
;                 const float wv = wp[(size_t)(hh * 64 + kk) * 6144];
; #pragma unroll
;                 for (int b = 0; b < 9; ++b) ac[b] += __int_as_float(__builtin_amdgcn_readlane(__float_as_int(sv[b][hh]), kk)) * wv;
	v_pk_fma_f32 v[12:13], v[98:99], s[18:19], v[12:13] op_sel_hi:[0,1,1]
	v_pk_fma_f32 v[10:11], v[98:99], s[20:21], v[10:11] op_sel_hi:[0,1,1]
	v_pk_fma_f32 v[8:9], v[98:99], s[22:23], v[8:9] op_sel_hi:[0,1,1]
	v_pk_fma_f32 v[6:7], v[98:99], s[24:25], v[6:7] op_sel_hi:[0,1,1]
	v_fmac_f32_e32 v2, s54, v98
	v_pk_fma_f32 v[12:13], v[100:101], s[0:1], v[12:13] op_sel_hi:[0,1,1]
	v_pk_fma_f32 v[10:11], v[100:101], s[26:27], v[10:11] op_sel_hi:[0,1,1]
	v_pk_fma_f32 v[8:9], v[100:101], s[28:29], v[8:9] op_sel_hi:[0,1,1]
	v_pk_fma_f32 v[6:7], v[100:101], s[30:31], v[6:7] op_sel_hi:[0,1,1]
	v_fmac_f32_e32 v2, s87, v100
	v_pk_fma_f32 v[12:13], v[102:103], s[34:35], v[12:13] op_sel_hi:[0,1,1]
	v_pk_fma_f32 v[10:11], v[102:103], s[36:37], v[10:11] op_sel_hi:[0,1,1]
	v_pk_fma_f32 v[8:9], v[102:103], s[38:39], v[8:9] op_sel_hi:[0,1,1]
	v_pk_fma_f32 v[6:7], v[102:103], s[40:41], v[6:7] op_sel_hi:[0,1,1]
	v_fmac_f32_e32 v2, s88, v102
	v_pk_fma_f32 v[12:13], v[104:105], s[42:43], v[12:13] op_sel_hi:[0,1,1]
	v_pk_fma_f32 v[10:11], v[104:105], s[44:45], v[10:11] op_sel_hi:[0,1,1]
	v_pk_fma_f32 v[8:9], v[104:105], s[46:47], v[8:9] op_sel_hi:[0,1,1]
	v_pk_fma_f32 v[6:7], v[104:105], s[48:49], v[6:7] op_sel_hi:[0,1,1]
	v_fmac_f32_e32 v2, s55, v104
	v_pk_fma_f32 v[12:13], v[106:107], s[58:59], v[12:13] op_sel_hi:[0,1,1]
	v_pk_fma_f32 v[10:11], v[106:107], s[60:61], v[10:11] op_sel_hi:[0,1,1]
	v_pk_fma_f32 v[8:9], v[106:107], s[62:63], v[8:9] op_sel_hi:[0,1,1]
	v_pk_fma_f32 v[6:7], v[106:107], s[64:65], v[6:7] op_sel_hi:[0,1,1]
	v_fmac_f32_e32 v2, s89, v106
	v_pk_fma_f32 v[12:13], v[108:109], s[56:57], v[12:13] op_sel_hi:[0,1,1]
	v_pk_fma_f32 v[10:11], v[108:109], s[66:67], v[10:11] op_sel_hi:[0,1,1]
	v_pk_fma_f32 v[8:9], v[108:109], s[68:69], v[8:9] op_sel_hi:[0,1,1]
	v_pk_fma_f32 v[6:7], v[108:109], s[70:71], v[6:7] op_sel_hi:[0,1,1]
	v_fmac_f32_e32 v2, s90, v108
	v_pk_fma_f32 v[12:13], v[110:111], s[12:13], v[12:13] op_sel_hi:[0,1,1]
	v_pk_fma_f32 v[10:11], v[110:111], s[72:73], v[10:11] op_sel_hi:[0,1,1]
	v_pk_fma_f32 v[8:9], v[110:111], s[74:75], v[8:9] op_sel_hi:[0,1,1]
	v_pk_fma_f32 v[6:7], v[110:111], s[76:77], v[6:7] op_sel_hi:[0,1,1]
	v_fmac_f32_e32 v2, s50, v110
	v_pk_fma_f32 v[12:13], v[112:113], s[78:79], v[12:13] op_sel_hi:[0,1,1]
	v_pk_fma_f32 v[10:11], v[112:113], s[80:81], v[10:11] op_sel_hi:[0,1,1]
	v_pk_fma_f32 v[8:9], v[112:113], s[82:83], v[8:9] op_sel_hi:[0,1,1]
	v_pk_fma_f32 v[6:7], v[112:113], s[84:85], v[6:7] op_sel_hi:[0,1,1]
	v_fmac_f32_e32 v2, s86, v112
	v_readlane_b32 s18, v29, 16
	v_readlane_b32 s19, v31, 16
	v_readlane_b32 s20, v26, 16
	v_readlane_b32 s21, v30, 16
	v_readlane_b32 s22, v24, 16
	v_readlane_b32 s23, v32, 16
	v_readlane_b32 s24, v23, 16
	v_readlane_b32 s25, v27, 16
	v_readlane_b32 s54, v25, 16
	v_readlane_b32 s0, v29, 17
	v_readlane_b32 s1, v31, 17
	v_readlane_b32 s26, v26, 17
	v_readlane_b32 s27, v30, 17
	v_readlane_b32 s28, v24, 17
	v_readlane_b32 s29, v32, 17
	v_readlane_b32 s30, v23, 17
	v_readlane_b32 s31, v27, 17
	v_readlane_b32 s87, v25, 17
	v_readlane_b32 s34, v29, 18
	v_readlane_b32 s35, v31, 18
	v_readlane_b32 s36, v26, 18
	v_readlane_b32 s37, v30, 18
	v_readlane_b32 s38, v24, 18
	v_readlane_b32 s39, v32, 18
	v_readlane_b32 s40, v23, 18
	v_readlane_b32 s41, v27, 18
	v_readlane_b32 s88, v25, 18
	v_readlane_b32 s42, v29, 19
	v_readlane_b32 s43, v31, 19
	v_readlane_b32 s44, v26, 19
	v_readlane_b32 s45, v30, 19
	v_readlane_b32 s46, v24, 19
	v_readlane_b32 s47, v32, 19
	v_readlane_b32 s48, v23, 19
	v_readlane_b32 s49, v27, 19
	v_readlane_b32 s55, v25, 19
	v_readlane_b32 s58, v29, 20
	v_readlane_b32 s59, v31, 20
	v_readlane_b32 s60, v26, 20
	v_readlane_b32 s61, v30, 20
	v_readlane_b32 s62, v24, 20
	v_readlane_b32 s63, v32, 20
	v_readlane_b32 s64, v23, 20
	v_readlane_b32 s65, v27, 20
	v_readlane_b32 s89, v25, 20
	v_readlane_b32 s56, v29, 21
	v_readlane_b32 s57, v31, 21
	v_readlane_b32 s66, v26, 21
	v_readlane_b32 s67, v30, 21
	v_readlane_b32 s68, v24, 21
	v_readlane_b32 s69, v32, 21
	v_readlane_b32 s70, v23, 21
	v_readlane_b32 s71, v27, 21
	v_readlane_b32 s90, v25, 21
	v_readlane_b32 s12, v29, 22
	v_readlane_b32 s13, v31, 22
	v_readlane_b32 s72, v26, 22
	v_readlane_b32 s73, v30, 22
	v_readlane_b32 s74, v24, 22
	v_readlane_b32 s75, v32, 22
	v_readlane_b32 s76, v23, 22
	v_readlane_b32 s77, v27, 22
	v_readlane_b32 s50, v25, 22
	v_readlane_b32 s78, v29, 23
	v_readlane_b32 s79, v31, 23
	v_readlane_b32 s80, v26, 23
	v_readlane_b32 s81, v30, 23
	v_readlane_b32 s82, v24, 23
	v_readlane_b32 s83, v32, 23
	v_readlane_b32 s84, v23, 23
	v_readlane_b32 s85, v27, 23
	v_readlane_b32 s86, v25, 23
	s_waitcnt vmcnt(40)
; __device__ __forceinline__ void prep_phase(const Params& p, LAS unsigned char* lds) {
;     ...
;         for (int hh = 0; hh < 2; ++hh) {
; #pragma unroll 8
;             for (int kk = 0; kk < 64; ++kk) {
;                 const float wv = wp[(size_t)(hh * 64 + kk) * 6144];
; #pragma unroll
;                 for (int b = 0; b < 9; ++b) ac[b] += __int_as_float(__builtin_amdgcn_readlane(__float_as_int(sv[b][hh]), kk)) * wv;
	v_pk_fma_f32 v[12:13], v[114:115], s[18:19], v[12:13] op_sel_hi:[0,1,1]
	v_pk_fma_f32 v[10:11], v[114:115], s[20:21], v[10:11] op_sel_hi:[0,1,1]
	v_pk_fma_f32 v[8:9], v[114:115], s[22:23], v[8:9] op_sel_hi:[0,1,1]
	v_pk_fma_f32 v[6:7], v[114:115], s[24:25], v[6:7] op_sel_hi:[0,1,1]
	v_fmac_f32_e32 v2, s54, v114
	v_pk_fma_f32 v[12:13], v[116:117], s[0:1], v[12:13] op_sel_hi:[0,1,1]
	v_pk_fma_f32 v[10:11], v[116:117], s[26:27], v[10:11] op_sel_hi:[0,1,1]
	v_pk_fma_f32 v[8:9], v[116:117], s[28:29], v[8:9] op_sel_hi:[0,1,1]
	v_pk_fma_f32 v[6:7], v[116:117], s[30:31], v[6:7] op_sel_hi:[0,1,1]
	v_fmac_f32_e32 v2, s87, v116
	v_pk_fma_f32 v[12:13], v[118:119], s[34:35], v[12:13] op_sel_hi:[0,1,1]
	v_pk_fma_f32 v[10:11], v[118:119], s[36:37], v[10:11] op_sel_hi:[0,1,1]
	v_pk_fma_f32 v[8:9], v[118:119], s[38:39], v[8:9] op_sel_hi:[0,1,1]
	v_pk_fma_f32 v[6:7], v[118:119], s[40:41], v[6:7] op_sel_hi:[0,1,1]
	v_fmac_f32_e32 v2, s88, v118
	v_pk_fma_f32 v[12:13], v[120:121], s[42:43], v[12:13] op_sel_hi:[0,1,1]
	v_pk_fma_f32 v[10:11], v[120:121], s[44:45], v[10:11] op_sel_hi:[0,1,1]
	v_pk_fma_f32 v[8:9], v[120:121], s[46:47], v[8:9] op_sel_hi:[0,1,1]
	v_pk_fma_f32 v[6:7], v[120:121], s[48:49], v[6:7] op_sel_hi:[0,1,1]
	v_fmac_f32_e32 v2, s55, v120
	v_pk_fma_f32 v[12:13], v[122:123], s[58:59], v[12:13] op_sel_hi:[0,1,1]
	v_pk_fma_f32 v[10:11], v[122:123], s[60:61], v[10:11] op_sel_hi:[0,1,1]
	v_pk_fma_f32 v[8:9], v[122:123], s[62:63], v[8:9] op_sel_hi:[0,1,1]
	v_pk_fma_f32 v[6:7], v[122:123], s[64:65], v[6:7] op_sel_hi:[0,1,1]
	v_fmac_f32_e32 v2, s89, v122
	v_pk_fma_f32 v[12:13], v[124:125], s[56:57], v[12:13] op_sel_hi:[0,1,1]
	v_pk_fma_f32 v[10:11], v[124:125], s[66:67], v[10:11] op_sel_hi:[0,1,1]
	v_pk_fma_f32 v[8:9], v[124:125], s[68:69], v[8:9] op_sel_hi:[0,1,1]
	v_pk_fma_f32 v[6:7], v[124:125], s[70:71], v[6:7] op_sel_hi:[0,1,1]
	v_fmac_f32_e32 v2, s90, v124
	v_pk_fma_f32 v[12:13], v[126:127], s[12:13], v[12:13] op_sel_hi:[0,1,1]
	v_pk_fma_f32 v[10:11], v[126:127], s[72:73], v[10:11] op_sel_hi:[0,1,1]
	v_pk_fma_f32 v[8:9], v[126:127], s[74:75], v[8:9] op_sel_hi:[0,1,1]
	v_pk_fma_f32 v[6:7], v[126:127], s[76:77], v[6:7] op_sel_hi:[0,1,1]
	v_fmac_f32_e32 v2, s50, v126
	v_pk_fma_f32 v[12:13], v[128:129], s[78:79], v[12:13] op_sel_hi:[0,1,1]
	v_pk_fma_f32 v[10:11], v[128:129], s[80:81], v[10:11] op_sel_hi:[0,1,1]
	v_pk_fma_f32 v[8:9], v[128:129], s[82:83], v[8:9] op_sel_hi:[0,1,1]
	v_pk_fma_f32 v[6:7], v[128:129], s[84:85], v[6:7] op_sel_hi:[0,1,1]
	v_fmac_f32_e32 v2, s86, v128
	v_readlane_b32 s18, v29, 24
	v_readlane_b32 s19, v31, 24
	v_readlane_b32 s20, v26, 24
	v_readlane_b32 s21, v30, 24
	v_readlane_b32 s22, v24, 24
	v_readlane_b32 s23, v32, 24
	v_readlane_b32 s24, v23, 24
	v_readlane_b32 s25, v27, 24
	v_readlane_b32 s54, v25, 24
	v_readlane_b32 s0, v29, 25
	v_readlane_b32 s1, v31, 25
	v_readlane_b32 s26, v26, 25
	v_readlane_b32 s27, v30, 25
	v_readlane_b32 s28, v24, 25
	v_readlane_b32 s29, v32, 25
	v_readlane_b32 s30, v23, 25
	v_readlane_b32 s31, v27, 25
	v_readlane_b32 s87, v25, 25
	v_readlane_b32 s34, v29, 26
	v_readlane_b32 s35, v31, 26
	v_readlane_b32 s36, v26, 26
	v_readlane_b32 s37, v30, 26
	v_readlane_b32 s38, v24, 26
	v_readlane_b32 s39, v32, 26
	v_readlane_b32 s40, v23, 26
	v_readlane_b32 s41, v27, 26
	v_readlane_b32 s88, v25, 26
	v_readlane_b32 s42, v29, 27
	v_readlane_b32 s43, v31, 27
	v_readlane_b32 s44, v26, 27
	v_readlane_b32 s45, v30, 27
	v_readlane_b32 s46, v24, 27
	v_readlane_b32 s47, v32, 27
	v_readlane_b32 s48, v23, 27
	v_readlane_b32 s49, v27, 27
	v_readlane_b32 s55, v25, 27
	v_readlane_b32 s58, v29, 28
	v_readlane_b32 s59, v31, 28
	v_readlane_b32 s60, v26, 28
	v_readlane_b32 s61, v30, 28
	v_readlane_b32 s62, v24, 28
	v_readlane_b32 s63, v32, 28
	v_readlane_b32 s64, v23, 28
	v_readlane_b32 s65, v27, 28
	v_readlane_b32 s89, v25, 28
	v_readlane_b32 s56, v29, 29
	v_readlane_b32 s57, v31, 29
	v_readlane_b32 s66, v26, 29
	v_readlane_b32 s67, v30, 29
	v_readlane_b32 s68, v24, 29
	v_readlane_b32 s69, v32, 29
	v_readlane_b32 s70, v23, 29
	v_readlane_b32 s71, v27, 29
	v_readlane_b32 s90, v25, 29
	v_readlane_b32 s12, v29, 30
	v_readlane_b32 s13, v31, 30
	v_readlane_b32 s72, v26, 30
	v_readlane_b32 s73, v30, 30
	v_readlane_b32 s74, v24, 30
	v_readlane_b32 s75, v32, 30
	v_readlane_b32 s76, v23, 30
	v_readlane_b32 s77, v27, 30
	v_readlane_b32 s50, v25, 30
	v_readlane_b32 s78, v29, 31
	v_readlane_b32 s79, v31, 31
	v_readlane_b32 s80, v26, 31
	v_readlane_b32 s81, v30, 31
	v_readlane_b32 s82, v24, 31
	v_readlane_b32 s83, v32, 31
	v_readlane_b32 s84, v23, 31
	v_readlane_b32 s85, v27, 31
	v_readlane_b32 s86, v25, 31
	s_waitcnt vmcnt(32)
; __device__ __forceinline__ void prep_phase(const Params& p, LAS unsigned char* lds) {
;     ...
;         for (int hh = 0; hh < 2; ++hh) {
; #pragma unroll 8
;             for (int kk = 0; kk < 64; ++kk) {
;                 const float wv = wp[(size_t)(hh * 64 + kk) * 6144];
; #pragma unroll
;                 for (int b = 0; b < 9; ++b) ac[b] += __int_as_float(__builtin_amdgcn_readlane(__float_as_int(sv[b][hh]), kk)) * wv;
;             }
;         }
	v_pk_fma_f32 v[12:13], v[130:131], s[18:19], v[12:13] op_sel_hi:[0,1,1]
	v_pk_fma_f32 v[10:11], v[130:131], s[20:21], v[10:11] op_sel_hi:[0,1,1]
	v_pk_fma_f32 v[8:9], v[130:131], s[22:23], v[8:9] op_sel_hi:[0,1,1]
	v_pk_fma_f32 v[6:7], v[130:131], s[24:25], v[6:7] op_sel_hi:[0,1,1]
	v_fmac_f32_e32 v2, s54, v130
	v_pk_fma_f32 v[12:13], v[132:133], s[0:1], v[12:13] op_sel_hi:[0,1,1]
	v_pk_fma_f32 v[10:11], v[132:133], s[26:27], v[10:11] op_sel_hi:[0,1,1]
	v_pk_fma_f32 v[8:9], v[132:133], s[28:29], v[8:9] op_sel_hi:[0,1,1]
	v_pk_fma_f32 v[6:7], v[132:133], s[30:31], v[6:7] op_sel_hi:[0,1,1]
	v_fmac_f32_e32 v2, s87, v132
	v_pk_fma_f32 v[12:13], v[134:135], s[34:35], v[12:13] op_sel_hi:[0,1,1]
	v_pk_fma_f32 v[10:11], v[134:135], s[36:37], v[10:11] op_sel_hi:[0,1,1]
	v_pk_fma_f32 v[8:9], v[134:135], s[38:39], v[8:9] op_sel_hi:[0,1,1]
	v_pk_fma_f32 v[6:7], v[134:135], s[40:41], v[6:7] op_sel_hi:[0,1,1]
	v_fmac_f32_e32 v2, s88, v134
	v_pk_fma_f32 v[12:13], v[136:137], s[42:43], v[12:13] op_sel_hi:[0,1,1]
	v_pk_fma_f32 v[10:11], v[136:137], s[44:45], v[10:11] op_sel_hi:[0,1,1]
	v_pk_fma_f32 v[8:9], v[136:137], s[46:47], v[8:9] op_sel_hi:[0,1,1]
	v_pk_fma_f32 v[6:7], v[136:137], s[48:49], v[6:7] op_sel_hi:[0,1,1]
	v_fmac_f32_e32 v2, s55, v136
	v_pk_fma_f32 v[12:13], v[138:139], s[58:59], v[12:13] op_sel_hi:[0,1,1]
	v_pk_fma_f32 v[10:11], v[138:139], s[60:61], v[10:11] op_sel_hi:[0,1,1]
	v_pk_fma_f32 v[8:9], v[138:139], s[62:63], v[8:9] op_sel_hi:[0,1,1]
	v_pk_fma_f32 v[6:7], v[138:139], s[64:65], v[6:7] op_sel_hi:[0,1,1]
	v_fmac_f32_e32 v2, s89, v138
	v_pk_fma_f32 v[12:13], v[140:141], s[56:57], v[12:13] op_sel_hi:[0,1,1]
	v_pk_fma_f32 v[10:11], v[140:141], s[66:67], v[10:11] op_sel_hi:[0,1,1]
	v_pk_fma_f32 v[8:9], v[140:141], s[68:69], v[8:9] op_sel_hi:[0,1,1]
	v_pk_fma_f32 v[6:7], v[140:141], s[70:71], v[6:7] op_sel_hi:[0,1,1]
	v_fmac_f32_e32 v2, s90, v140
	v_pk_fma_f32 v[12:13], v[142:143], s[12:13], v[12:13] op_sel_hi:[0,1,1]
	v_pk_fma_f32 v[10:11], v[142:143], s[72:73], v[10:11] op_sel_hi:[0,1,1]
	v_pk_fma_f32 v[8:9], v[142:143], s[74:75], v[8:9] op_sel_hi:[0,1,1]
	v_pk_fma_f32 v[6:7], v[142:143], s[76:77], v[6:7] op_sel_hi:[0,1,1]
	v_fmac_f32_e32 v2, s50, v142
	v_pk_fma_f32 v[12:13], v[144:145], s[78:79], v[12:13] op_sel_hi:[0,1,1]
	v_pk_fma_f32 v[10:11], v[144:145], s[80:81], v[10:11] op_sel_hi:[0,1,1]
	v_pk_fma_f32 v[8:9], v[144:145], s[82:83], v[8:9] op_sel_hi:[0,1,1]
	v_pk_fma_f32 v[6:7], v[144:145], s[84:85], v[6:7] op_sel_hi:[0,1,1]
	v_fmac_f32_e32 v2, s86, v144
	v_readlane_b32 s18, v29, 32
	v_readlane_b32 s19, v31, 32
	v_readlane_b32 s20, v26, 32
	v_readlane_b32 s21, v30, 32
	v_readlane_b32 s22, v24, 32
	v_readlane_b32 s23, v32, 32
	v_readlane_b32 s24, v23, 32
	v_readlane_b32 s25, v27, 32
	v_readlane_b32 s54, v25, 32
	v_readlane_b32 s0, v29, 33
	v_readlane_b32 s1, v31, 33
	v_readlane_b32 s26, v26, 33
	v_readlane_b32 s27, v30, 33
	v_readlane_b32 s28, v24, 33
	v_readlane_b32 s29, v32, 33
	v_readlane_b32 s30, v23, 33
	v_readlane_b32 s31, v27, 33
	v_readlane_b32 s87, v25, 33
	v_readlane_b32 s34, v29, 34
	v_readlane_b32 s35, v31, 34
	v_readlane_b32 s36, v26, 34
	v_readlane_b32 s37, v30, 34
	v_readlane_b32 s38, v24, 34
	v_readlane_b32 s39, v32, 34
	v_readlane_b32 s40, v23, 34
	v_readlane_b32 s41, v27, 34
	v_readlane_b32 s88, v25, 34
	v_readlane_b32 s42, v29, 35
	v_readlane_b32 s43, v31, 35
	v_readlane_b32 s44, v26, 35
	v_readlane_b32 s45, v30, 35
	v_readlane_b32 s46, v24, 35
	v_readlane_b32 s47, v32, 35
	v_readlane_b32 s48, v23, 35
	v_readlane_b32 s49, v27, 35
	v_readlane_b32 s55, v25, 35
	v_readlane_b32 s58, v29, 36
	v_readlane_b32 s59, v31, 36
	v_readlane_b32 s60, v26, 36
	v_readlane_b32 s61, v30, 36
	v_readlane_b32 s62, v24, 36
	v_readlane_b32 s63, v32, 36
	v_readlane_b32 s64, v23, 36
	v_readlane_b32 s65, v27, 36
	v_readlane_b32 s89, v25, 36
	v_readlane_b32 s56, v29, 37
	v_readlane_b32 s57, v31, 37
	v_readlane_b32 s66, v26, 37
	v_readlane_b32 s67, v30, 37
	v_readlane_b32 s68, v24, 37
	v_readlane_b32 s69, v32, 37
	v_readlane_b32 s70, v23, 37
	v_readlane_b32 s71, v27, 37
	v_readlane_b32 s90, v25, 37
	v_readlane_b32 s12, v29, 38
	v_readlane_b32 s13, v31, 38
	v_readlane_b32 s72, v26, 38
	v_readlane_b32 s73, v30, 38
	v_readlane_b32 s74, v24, 38
	v_readlane_b32 s75, v32, 38
	v_readlane_b32 s76, v23, 38
	v_readlane_b32 s77, v27, 38
	v_readlane_b32 s50, v25, 38
	v_readlane_b32 s78, v29, 39
	v_readlane_b32 s79, v31, 39
	v_readlane_b32 s80, v26, 39
	v_readlane_b32 s81, v30, 39
	v_readlane_b32 s82, v24, 39
	v_readlane_b32 s83, v32, 39
	v_readlane_b32 s84, v23, 39
	v_readlane_b32 s85, v27, 39
	v_readlane_b32 s86, v25, 39
	s_waitcnt vmcnt(24)
; __device__ __forceinline__ void prep_phase(const Params& p, LAS unsigned char* lds) {
;     ...
;         for (int hh = 0; hh < 2; ++hh) {
; #pragma unroll 8
;             for (int kk = 0; kk < 64; ++kk) {
;                 const float wv = wp[(size_t)(hh * 64 + kk) * 6144];
; #pragma unroll
;                 for (int b = 0; b < 9; ++b) ac[b] += __int_as_float(__builtin_amdgcn_readlane(__float_as_int(sv[b][hh]), kk)) * wv;
;             }
;         }
	v_pk_fma_f32 v[12:13], v[146:147], s[18:19], v[12:13] op_sel_hi:[0,1,1]
	v_pk_fma_f32 v[10:11], v[146:147], s[20:21], v[10:11] op_sel_hi:[0,1,1]
	v_pk_fma_f32 v[8:9], v[146:147], s[22:23], v[8:9] op_sel_hi:[0,1,1]
	v_pk_fma_f32 v[6:7], v[146:147], s[24:25], v[6:7] op_sel_hi:[0,1,1]
	v_fmac_f32_e32 v2, s54, v146
	v_pk_fma_f32 v[12:13], v[148:149], s[0:1], v[12:13] op_sel_hi:[0,1,1]
	v_pk_fma_f32 v[10:11], v[148:149], s[26:27], v[10:11] op_sel_hi:[0,1,1]
	v_pk_fma_f32 v[8:9], v[148:149], s[28:29], v[8:9] op_sel_hi:[0,1,1]
	v_pk_fma_f32 v[6:7], v[148:149], s[30:31], v[6:7] op_sel_hi:[0,1,1]
	v_fmac_f32_e32 v2, s87, v148
	v_pk_fma_f32 v[12:13], v[150:151], s[34:35], v[12:13] op_sel_hi:[0,1,1]
	v_pk_fma_f32 v[10:11], v[150:151], s[36:37], v[10:11] op_sel_hi:[0,1,1]
	v_pk_fma_f32 v[8:9], v[150:151], s[38:39], v[8:9] op_sel_hi:[0,1,1]
	v_pk_fma_f32 v[6:7], v[150:151], s[40:41], v[6:7] op_sel_hi:[0,1,1]
	v_fmac_f32_e32 v2, s88, v150
	v_pk_fma_f32 v[12:13], v[152:153], s[42:43], v[12:13] op_sel_hi:[0,1,1]
	v_pk_fma_f32 v[10:11], v[152:153], s[44:45], v[10:11] op_sel_hi:[0,1,1]
	v_pk_fma_f32 v[8:9], v[152:153], s[46:47], v[8:9] op_sel_hi:[0,1,1]
	v_pk_fma_f32 v[6:7], v[152:153], s[48:49], v[6:7] op_sel_hi:[0,1,1]
	v_fmac_f32_e32 v2, s55, v152
	v_pk_fma_f32 v[12:13], v[154:155], s[58:59], v[12:13] op_sel_hi:[0,1,1]
	v_pk_fma_f32 v[10:11], v[154:155], s[60:61], v[10:11] op_sel_hi:[0,1,1]
	v_pk_fma_f32 v[8:9], v[154:155], s[62:63], v[8:9] op_sel_hi:[0,1,1]
	v_pk_fma_f32 v[6:7], v[154:155], s[64:65], v[6:7] op_sel_hi:[0,1,1]
	v_fmac_f32_e32 v2, s89, v154
	v_pk_fma_f32 v[12:13], v[158:159], s[56:57], v[12:13] op_sel_hi:[0,1,1]
	v_pk_fma_f32 v[10:11], v[158:159], s[66:67], v[10:11] op_sel_hi:[0,1,1]
	v_pk_fma_f32 v[8:9], v[158:159], s[68:69], v[8:9] op_sel_hi:[0,1,1]
	v_pk_fma_f32 v[6:7], v[158:159], s[70:71], v[6:7] op_sel_hi:[0,1,1]
	v_fmac_f32_e32 v2, s90, v158
	v_pk_fma_f32 v[12:13], v[160:161], s[12:13], v[12:13] op_sel_hi:[0,1,1]
	v_pk_fma_f32 v[10:11], v[160:161], s[72:73], v[10:11] op_sel_hi:[0,1,1]
	v_pk_fma_f32 v[8:9], v[160:161], s[74:75], v[8:9] op_sel_hi:[0,1,1]
	v_pk_fma_f32 v[6:7], v[160:161], s[76:77], v[6:7] op_sel_hi:[0,1,1]
	v_fmac_f32_e32 v2, s50, v160
	v_pk_fma_f32 v[12:13], v[162:163], s[78:79], v[12:13] op_sel_hi:[0,1,1]
	v_pk_fma_f32 v[10:11], v[162:163], s[80:81], v[10:11] op_sel_hi:[0,1,1]
	v_pk_fma_f32 v[8:9], v[162:163], s[82:83], v[8:9] op_sel_hi:[0,1,1]
	v_pk_fma_f32 v[6:7], v[162:163], s[84:85], v[6:7] op_sel_hi:[0,1,1]
	v_fmac_f32_e32 v2, s86, v162
	v_readlane_b32 s18, v29, 40
	v_readlane_b32 s19, v31, 40
	v_readlane_b32 s20, v26, 40
	v_readlane_b32 s21, v30, 40
	v_readlane_b32 s22, v24, 40
	v_readlane_b32 s23, v32, 40
	v_readlane_b32 s24, v23, 40
	v_readlane_b32 s25, v27, 40
	v_readlane_b32 s54, v25, 40
	v_readlane_b32 s0, v29, 41
	v_readlane_b32 s1, v31, 41
	v_readlane_b32 s26, v26, 41
	v_readlane_b32 s27, v30, 41
	v_readlane_b32 s28, v24, 41
	v_readlane_b32 s29, v32, 41
	v_readlane_b32 s30, v23, 41
	v_readlane_b32 s31, v27, 41
	v_readlane_b32 s87, v25, 41
	v_readlane_b32 s34, v29, 42
	v_readlane_b32 s35, v31, 42
	v_readlane_b32 s36, v26, 42
	v_readlane_b32 s37, v30, 42
	v_readlane_b32 s38, v24, 42
	v_readlane_b32 s39, v32, 42
	v_readlane_b32 s40, v23, 42
	v_readlane_b32 s41, v27, 42
	v_readlane_b32 s88, v25, 42
	v_readlane_b32 s42, v29, 43
	v_readlane_b32 s43, v31, 43
	v_readlane_b32 s44, v26, 43
	v_readlane_b32 s45, v30, 43
	v_readlane_b32 s46, v24, 43
	v_readlane_b32 s47, v32, 43
	v_readlane_b32 s48, v23, 43
	v_readlane_b32 s49, v27, 43
	v_readlane_b32 s55, v25, 43
	v_readlane_b32 s58, v29, 44
	v_readlane_b32 s59, v31, 44
	v_readlane_b32 s60, v26, 44
	v_readlane_b32 s61, v30, 44
	v_readlane_b32 s62, v24, 44
	v_readlane_b32 s63, v32, 44
	v_readlane_b32 s64, v23, 44
	v_readlane_b32 s65, v27, 44
	v_readlane_b32 s89, v25, 44
	v_readlane_b32 s56, v29, 45
	v_readlane_b32 s57, v31, 45
	v_readlane_b32 s66, v26, 45
	v_readlane_b32 s67, v30, 45
	v_readlane_b32 s68, v24, 45
	v_readlane_b32 s69, v32, 45
	v_readlane_b32 s70, v23, 45
	v_readlane_b32 s71, v27, 45
	v_readlane_b32 s90, v25, 45
	v_readlane_b32 s12, v29, 46
	v_readlane_b32 s13, v31, 46
	v_readlane_b32 s72, v26, 46
	v_readlane_b32 s73, v30, 46
	v_readlane_b32 s74, v24, 46
	v_readlane_b32 s75, v32, 46
	v_readlane_b32 s76, v23, 46
	v_readlane_b32 s77, v27, 46
	v_readlane_b32 s50, v25, 46
	v_readlane_b32 s78, v29, 47
	v_readlane_b32 s79, v31, 47
	v_readlane_b32 s80, v26, 47
	v_readlane_b32 s81, v30, 47
	v_readlane_b32 s82, v24, 47
	v_readlane_b32 s83, v32, 47
	v_readlane_b32 s84, v23, 47
	v_readlane_b32 s85, v27, 47
	v_readlane_b32 s86, v25, 47
	s_waitcnt vmcnt(16)
; __device__ __forceinline__ void prep_phase(const Params& p, LAS unsigned char* lds) {
;     ...
;         for (int hh = 0; hh < 2; ++hh) {
; #pragma unroll 8
;             for (int kk = 0; kk < 64; ++kk) {
;                 const float wv = wp[(size_t)(hh * 64 + kk) * 6144];
; #pragma unroll
;                 for (int b = 0; b < 9; ++b) ac[b] += __int_as_float(__builtin_amdgcn_readlane(__float_as_int(sv[b][hh]), kk)) * wv;
;             }
;         }
	v_pk_fma_f32 v[12:13], v[164:165], s[18:19], v[12:13] op_sel_hi:[0,1,1]
	v_pk_fma_f32 v[10:11], v[164:165], s[20:21], v[10:11] op_sel_hi:[0,1,1]
	v_pk_fma_f32 v[8:9], v[164:165], s[22:23], v[8:9] op_sel_hi:[0,1,1]
	v_pk_fma_f32 v[6:7], v[164:165], s[24:25], v[6:7] op_sel_hi:[0,1,1]
	v_fmac_f32_e32 v2, s54, v164
	v_pk_fma_f32 v[12:13], v[166:167], s[0:1], v[12:13] op_sel_hi:[0,1,1]
	v_pk_fma_f32 v[10:11], v[166:167], s[26:27], v[10:11] op_sel_hi:[0,1,1]
	v_pk_fma_f32 v[8:9], v[166:167], s[28:29], v[8:9] op_sel_hi:[0,1,1]
	v_pk_fma_f32 v[6:7], v[166:167], s[30:31], v[6:7] op_sel_hi:[0,1,1]
	v_fmac_f32_e32 v2, s87, v166
	v_pk_fma_f32 v[12:13], v[168:169], s[34:35], v[12:13] op_sel_hi:[0,1,1]
	v_pk_fma_f32 v[10:11], v[168:169], s[36:37], v[10:11] op_sel_hi:[0,1,1]
	v_pk_fma_f32 v[8:9], v[168:169], s[38:39], v[8:9] op_sel_hi:[0,1,1]
	v_pk_fma_f32 v[6:7], v[168:169], s[40:41], v[6:7] op_sel_hi:[0,1,1]
	v_fmac_f32_e32 v2, s88, v168
	v_pk_fma_f32 v[12:13], v[170:171], s[42:43], v[12:13] op_sel_hi:[0,1,1]
	v_pk_fma_f32 v[10:11], v[170:171], s[44:45], v[10:11] op_sel_hi:[0,1,1]
	v_pk_fma_f32 v[8:9], v[170:171], s[46:47], v[8:9] op_sel_hi:[0,1,1]
	v_pk_fma_f32 v[6:7], v[170:171], s[48:49], v[6:7] op_sel_hi:[0,1,1]
	v_fmac_f32_e32 v2, s55, v170
	v_pk_fma_f32 v[12:13], v[172:173], s[58:59], v[12:13] op_sel_hi:[0,1,1]
	v_pk_fma_f32 v[10:11], v[172:173], s[60:61], v[10:11] op_sel_hi:[0,1,1]
	v_pk_fma_f32 v[8:9], v[172:173], s[62:63], v[8:9] op_sel_hi:[0,1,1]
	v_pk_fma_f32 v[6:7], v[172:173], s[64:65], v[6:7] op_sel_hi:[0,1,1]
	v_fmac_f32_e32 v2, s89, v172
	v_pk_fma_f32 v[12:13], v[174:175], s[56:57], v[12:13] op_sel_hi:[0,1,1]
	v_pk_fma_f32 v[10:11], v[174:175], s[66:67], v[10:11] op_sel_hi:[0,1,1]
	v_pk_fma_f32 v[8:9], v[174:175], s[68:69], v[8:9] op_sel_hi:[0,1,1]
	v_pk_fma_f32 v[6:7], v[174:175], s[70:71], v[6:7] op_sel_hi:[0,1,1]
	v_fmac_f32_e32 v2, s90, v174
	v_pk_fma_f32 v[12:13], v[176:177], s[12:13], v[12:13] op_sel_hi:[0,1,1]
	v_pk_fma_f32 v[10:11], v[176:177], s[72:73], v[10:11] op_sel_hi:[0,1,1]
	v_pk_fma_f32 v[8:9], v[176:177], s[74:75], v[8:9] op_sel_hi:[0,1,1]
	v_pk_fma_f32 v[6:7], v[176:177], s[76:77], v[6:7] op_sel_hi:[0,1,1]
	v_fmac_f32_e32 v2, s50, v176
	v_pk_fma_f32 v[12:13], v[178:179], s[78:79], v[12:13] op_sel_hi:[0,1,1]
	v_pk_fma_f32 v[10:11], v[178:179], s[80:81], v[10:11] op_sel_hi:[0,1,1]
	v_pk_fma_f32 v[8:9], v[178:179], s[82:83], v[8:9] op_sel_hi:[0,1,1]
	v_pk_fma_f32 v[6:7], v[178:179], s[84:85], v[6:7] op_sel_hi:[0,1,1]
	v_fmac_f32_e32 v2, s86, v178
	v_readlane_b32 s18, v29, 48
	v_readlane_b32 s19, v31, 48
	v_readlane_b32 s20, v26, 48
	v_readlane_b32 s21, v30, 48
	v_readlane_b32 s22, v24, 48
	v_readlane_b32 s23, v32, 48
	v_readlane_b32 s24, v23, 48
	v_readlane_b32 s25, v27, 48
	v_readlane_b32 s54, v25, 48
	v_readlane_b32 s0, v29, 49
	v_readlane_b32 s1, v31, 49
	v_readlane_b32 s26, v26, 49
	v_readlane_b32 s27, v30, 49
	v_readlane_b32 s28, v24, 49
	v_readlane_b32 s29, v32, 49
	v_readlane_b32 s30, v23, 49
	v_readlane_b32 s31, v27, 49
	v_readlane_b32 s87, v25, 49
	v_readlane_b32 s34, v29, 50
	v_readlane_b32 s35, v31, 50
	v_readlane_b32 s36, v26, 50
	v_readlane_b32 s37, v30, 50
	v_readlane_b32 s38, v24, 50
	v_readlane_b32 s39, v32, 50
	v_readlane_b32 s40, v23, 50
	v_readlane_b32 s41, v27, 50
	v_readlane_b32 s88, v25, 50
	v_readlane_b32 s42, v29, 51
	v_readlane_b32 s43, v31, 51
	v_readlane_b32 s44, v26, 51
	v_readlane_b32 s45, v30, 51
	v_readlane_b32 s46, v24, 51
	v_readlane_b32 s47, v32, 51
	v_readlane_b32 s48, v23, 51
	v_readlane_b32 s49, v27, 51
	v_readlane_b32 s55, v25, 51
	v_readlane_b32 s58, v29, 52
	v_readlane_b32 s59, v31, 52
	v_readlane_b32 s60, v26, 52
	v_readlane_b32 s61, v30, 52
	v_readlane_b32 s62, v24, 52
	v_readlane_b32 s63, v32, 52
	v_readlane_b32 s64, v23, 52
	v_readlane_b32 s65, v27, 52
	v_readlane_b32 s89, v25, 52
	v_readlane_b32 s56, v29, 53
	v_readlane_b32 s57, v31, 53
	v_readlane_b32 s66, v26, 53
	v_readlane_b32 s67, v30, 53
	v_readlane_b32 s68, v24, 53
	v_readlane_b32 s69, v32, 53
	v_readlane_b32 s70, v23, 53
	v_readlane_b32 s71, v27, 53
	v_readlane_b32 s90, v25, 53
	v_readlane_b32 s12, v29, 54
	v_readlane_b32 s13, v31, 54
	v_readlane_b32 s72, v26, 54
	v_readlane_b32 s73, v30, 54
	v_readlane_b32 s74, v24, 54
	v_readlane_b32 s75, v32, 54
	v_readlane_b32 s76, v23, 54
	v_readlane_b32 s77, v27, 54
	v_readlane_b32 s50, v25, 54
	v_readlane_b32 s78, v29, 55
	v_readlane_b32 s79, v31, 55
	v_readlane_b32 s80, v26, 55
	v_readlane_b32 s81, v30, 55
	v_readlane_b32 s82, v24, 55
	v_readlane_b32 s83, v32, 55
	v_readlane_b32 s84, v23, 55
	v_readlane_b32 s85, v27, 55
	v_readlane_b32 s86, v25, 55
	s_waitcnt vmcnt(8)
; __device__ __forceinline__ void prep_phase(const Params& p, LAS unsigned char* lds) {
;     ...
;         for (int hh = 0; hh < 2; ++hh) {
; #pragma unroll 8
;             for (int kk = 0; kk < 64; ++kk) {
;                 const float wv = wp[(size_t)(hh * 64 + kk) * 6144];
; #pragma unroll
;                 for (int b = 0; b < 9; ++b) ac[b] += __int_as_float(__builtin_amdgcn_readlane(__float_as_int(sv[b][hh]), kk)) * wv;
;             }
;         }
	v_pk_fma_f32 v[12:13], v[180:181], s[18:19], v[12:13] op_sel_hi:[0,1,1]
	v_pk_fma_f32 v[10:11], v[180:181], s[20:21], v[10:11] op_sel_hi:[0,1,1]
	v_pk_fma_f32 v[8:9], v[180:181], s[22:23], v[8:9] op_sel_hi:[0,1,1]
	v_pk_fma_f32 v[6:7], v[180:181], s[24:25], v[6:7] op_sel_hi:[0,1,1]
	v_fmac_f32_e32 v2, s54, v180
	v_pk_fma_f32 v[12:13], v[182:183], s[0:1], v[12:13] op_sel_hi:[0,1,1]
	v_pk_fma_f32 v[10:11], v[182:183], s[26:27], v[10:11] op_sel_hi:[0,1,1]
	v_pk_fma_f32 v[8:9], v[182:183], s[28:29], v[8:9] op_sel_hi:[0,1,1]
	v_pk_fma_f32 v[6:7], v[182:183], s[30:31], v[6:7] op_sel_hi:[0,1,1]
	v_fmac_f32_e32 v2, s87, v182
	v_pk_fma_f32 v[12:13], v[184:185], s[34:35], v[12:13] op_sel_hi:[0,1,1]
	v_pk_fma_f32 v[10:11], v[184:185], s[36:37], v[10:11] op_sel_hi:[0,1,1]
	v_pk_fma_f32 v[8:9], v[184:185], s[38:39], v[8:9] op_sel_hi:[0,1,1]
	v_pk_fma_f32 v[6:7], v[184:185], s[40:41], v[6:7] op_sel_hi:[0,1,1]
	v_fmac_f32_e32 v2, s88, v184
	v_pk_fma_f32 v[12:13], v[186:187], s[42:43], v[12:13] op_sel_hi:[0,1,1]
	v_pk_fma_f32 v[10:11], v[186:187], s[44:45], v[10:11] op_sel_hi:[0,1,1]
	v_pk_fma_f32 v[8:9], v[186:187], s[46:47], v[8:9] op_sel_hi:[0,1,1]
	v_pk_fma_f32 v[6:7], v[186:187], s[48:49], v[6:7] op_sel_hi:[0,1,1]
	v_fmac_f32_e32 v2, s55, v186
	v_pk_fma_f32 v[12:13], v[188:189], s[58:59], v[12:13] op_sel_hi:[0,1,1]
	v_pk_fma_f32 v[10:11], v[188:189], s[60:61], v[10:11] op_sel_hi:[0,1,1]
	v_pk_fma_f32 v[8:9], v[188:189], s[62:63], v[8:9] op_sel_hi:[0,1,1]
	v_pk_fma_f32 v[6:7], v[188:189], s[64:65], v[6:7] op_sel_hi:[0,1,1]
	v_fmac_f32_e32 v2, s89, v188
	v_pk_fma_f32 v[12:13], v[190:191], s[56:57], v[12:13] op_sel_hi:[0,1,1]
	v_pk_fma_f32 v[10:11], v[190:191], s[66:67], v[10:11] op_sel_hi:[0,1,1]
	v_pk_fma_f32 v[8:9], v[190:191], s[68:69], v[8:9] op_sel_hi:[0,1,1]
	v_pk_fma_f32 v[6:7], v[190:191], s[70:71], v[6:7] op_sel_hi:[0,1,1]
	v_fmac_f32_e32 v2, s90, v190
	v_pk_fma_f32 v[12:13], v[194:195], s[12:13], v[12:13] op_sel_hi:[0,1,1]
	v_pk_fma_f32 v[10:11], v[194:195], s[72:73], v[10:11] op_sel_hi:[0,1,1]
	v_pk_fma_f32 v[8:9], v[194:195], s[74:75], v[8:9] op_sel_hi:[0,1,1]
	v_pk_fma_f32 v[6:7], v[194:195], s[76:77], v[6:7] op_sel_hi:[0,1,1]
	v_fmac_f32_e32 v2, s50, v194
	v_pk_fma_f32 v[12:13], v[196:197], s[78:79], v[12:13] op_sel_hi:[0,1,1]
	v_pk_fma_f32 v[10:11], v[196:197], s[80:81], v[10:11] op_sel_hi:[0,1,1]
	v_pk_fma_f32 v[8:9], v[196:197], s[82:83], v[8:9] op_sel_hi:[0,1,1]
	v_pk_fma_f32 v[6:7], v[196:197], s[84:85], v[6:7] op_sel_hi:[0,1,1]
	v_fmac_f32_e32 v2, s86, v196
	v_readlane_b32 s18, v29, 56
	v_readlane_b32 s19, v31, 56
	v_readlane_b32 s20, v26, 56
	v_readlane_b32 s21, v30, 56
	v_readlane_b32 s22, v24, 56
	v_readlane_b32 s23, v32, 56
	v_readlane_b32 s24, v23, 56
	v_readlane_b32 s25, v27, 56
	v_readlane_b32 s54, v25, 56
	v_readlane_b32 s0, v29, 57
	v_readlane_b32 s1, v31, 57
	v_readlane_b32 s26, v26, 57
	v_readlane_b32 s27, v30, 57
	v_readlane_b32 s28, v24, 57
	v_readlane_b32 s29, v32, 57
	v_readlane_b32 s30, v23, 57
	v_readlane_b32 s31, v27, 57
	v_readlane_b32 s87, v25, 57
	v_readlane_b32 s34, v29, 58
	v_readlane_b32 s35, v31, 58
	v_readlane_b32 s36, v26, 58
	v_readlane_b32 s37, v30, 58
	v_readlane_b32 s38, v24, 58
	v_readlane_b32 s39, v32, 58
	v_readlane_b32 s40, v23, 58
	v_readlane_b32 s41, v27, 58
	v_readlane_b32 s88, v25, 58
	v_readlane_b32 s42, v29, 59
	v_readlane_b32 s43, v31, 59
	v_readlane_b32 s44, v26, 59
	v_readlane_b32 s45, v30, 59
	v_readlane_b32 s46, v24, 59
	v_readlane_b32 s47, v32, 59
	v_readlane_b32 s48, v23, 59
	v_readlane_b32 s49, v27, 59
	v_readlane_b32 s55, v25, 59
	v_readlane_b32 s58, v29, 60
	v_readlane_b32 s59, v31, 60
	v_readlane_b32 s60, v26, 60
	v_readlane_b32 s61, v30, 60
	v_readlane_b32 s62, v24, 60
	v_readlane_b32 s63, v32, 60
	v_readlane_b32 s64, v23, 60
	v_readlane_b32 s65, v27, 60
	v_readlane_b32 s89, v25, 60
	v_readlane_b32 s56, v29, 61
	v_readlane_b32 s57, v31, 61
	v_readlane_b32 s66, v26, 61
	v_readlane_b32 s67, v30, 61
	v_readlane_b32 s68, v24, 61
	v_readlane_b32 s69, v32, 61
	v_readlane_b32 s70, v23, 61
	v_readlane_b32 s71, v27, 61
	v_readlane_b32 s90, v25, 61
	v_readlane_b32 s12, v29, 62
	v_readlane_b32 s13, v31, 62
	v_readlane_b32 s72, v26, 62
	v_readlane_b32 s73, v30, 62
	v_readlane_b32 s74, v24, 62
	v_readlane_b32 s75, v32, 62
	v_readlane_b32 s76, v23, 62
	v_readlane_b32 s77, v27, 62
	v_readlane_b32 s50, v25, 62
	v_readlane_b32 s78, v29, 63
	v_readlane_b32 s79, v31, 63
	v_readlane_b32 s80, v26, 63
	v_readlane_b32 s81, v30, 63
	v_readlane_b32 s82, v24, 63
	v_readlane_b32 s83, v32, 63
	v_readlane_b32 s84, v23, 63
	v_readlane_b32 s85, v27, 63
	v_readlane_b32 s86, v25, 63
	s_waitcnt vmcnt(0)
; __device__ __forceinline__ void prep_phase(const Params& p, LAS unsigned char* lds) {
;     ...
;         for (int hh = 0; hh < 2; ++hh) {
; #pragma unroll 8
;             for (int kk = 0; kk < 64; ++kk) {
;                 const float wv = wp[(size_t)(hh * 64 + kk) * 6144];
; #pragma unroll
;                 for (int b = 0; b < 9; ++b) ac[b] += __int_as_float(__builtin_amdgcn_readlane(__float_as_int(sv[b][hh]), kk)) * wv;
;             }
;         }
;         const float bias = (kc == 0) ? p.b_ada[l * 6144 + col] : 0.f;
	v_pk_fma_f32 v[12:13], v[198:199], s[18:19], v[12:13] op_sel_hi:[0,1,1]
	v_pk_fma_f32 v[10:11], v[198:199], s[20:21], v[10:11] op_sel_hi:[0,1,1]
	v_pk_fma_f32 v[8:9], v[198:199], s[22:23], v[8:9] op_sel_hi:[0,1,1]
	v_pk_fma_f32 v[6:7], v[198:199], s[24:25], v[6:7] op_sel_hi:[0,1,1]
	v_fmac_f32_e32 v2, s54, v198
	v_pk_fma_f32 v[12:13], v[202:203], s[0:1], v[12:13] op_sel_hi:[0,1,1]
	v_pk_fma_f32 v[10:11], v[202:203], s[26:27], v[10:11] op_sel_hi:[0,1,1]
	v_pk_fma_f32 v[8:9], v[202:203], s[28:29], v[8:9] op_sel_hi:[0,1,1]
	v_pk_fma_f32 v[6:7], v[202:203], s[30:31], v[6:7] op_sel_hi:[0,1,1]
	v_fmac_f32_e32 v2, s87, v202
	v_pk_fma_f32 v[12:13], v[204:205], s[34:35], v[12:13] op_sel_hi:[0,1,1]
	v_pk_fma_f32 v[10:11], v[204:205], s[36:37], v[10:11] op_sel_hi:[0,1,1]
	v_pk_fma_f32 v[8:9], v[204:205], s[38:39], v[8:9] op_sel_hi:[0,1,1]
	v_pk_fma_f32 v[6:7], v[204:205], s[40:41], v[6:7] op_sel_hi:[0,1,1]
	v_fmac_f32_e32 v2, s88, v204
	v_pk_fma_f32 v[12:13], v[206:207], s[42:43], v[12:13] op_sel_hi:[0,1,1]
	v_pk_fma_f32 v[10:11], v[206:207], s[44:45], v[10:11] op_sel_hi:[0,1,1]
	v_pk_fma_f32 v[8:9], v[206:207], s[46:47], v[8:9] op_sel_hi:[0,1,1]
	v_pk_fma_f32 v[6:7], v[206:207], s[48:49], v[6:7] op_sel_hi:[0,1,1]
	v_fmac_f32_e32 v2, s55, v206
	v_pk_fma_f32 v[12:13], v[208:209], s[58:59], v[12:13] op_sel_hi:[0,1,1]
	v_pk_fma_f32 v[10:11], v[208:209], s[60:61], v[10:11] op_sel_hi:[0,1,1]
	v_pk_fma_f32 v[8:9], v[208:209], s[62:63], v[8:9] op_sel_hi:[0,1,1]
	v_pk_fma_f32 v[6:7], v[208:209], s[64:65], v[6:7] op_sel_hi:[0,1,1]
	v_fmac_f32_e32 v2, s89, v208
	v_pk_fma_f32 v[12:13], v[210:211], s[56:57], v[12:13] op_sel_hi:[0,1,1]
	v_pk_fma_f32 v[10:11], v[210:211], s[66:67], v[10:11] op_sel_hi:[0,1,1]
	v_pk_fma_f32 v[8:9], v[210:211], s[68:69], v[8:9] op_sel_hi:[0,1,1]
	v_pk_fma_f32 v[6:7], v[210:211], s[70:71], v[6:7] op_sel_hi:[0,1,1]
	v_fmac_f32_e32 v2, s90, v210
	v_pk_fma_f32 v[12:13], v[212:213], s[12:13], v[12:13] op_sel_hi:[0,1,1]
	v_pk_fma_f32 v[10:11], v[212:213], s[72:73], v[10:11] op_sel_hi:[0,1,1]
	v_pk_fma_f32 v[8:9], v[212:213], s[74:75], v[8:9] op_sel_hi:[0,1,1]
	v_pk_fma_f32 v[6:7], v[212:213], s[76:77], v[6:7] op_sel_hi:[0,1,1]
	v_fmac_f32_e32 v2, s50, v212
	v_pk_fma_f32 v[12:13], v[214:215], s[78:79], v[12:13] op_sel_hi:[0,1,1]
	v_pk_fma_f32 v[10:11], v[214:215], s[80:81], v[10:11] op_sel_hi:[0,1,1]
	v_pk_fma_f32 v[8:9], v[214:215], s[82:83], v[8:9] op_sel_hi:[0,1,1]
	v_pk_fma_f32 v[6:7], v[214:215], s[84:85], v[6:7] op_sel_hi:[0,1,1]
	v_fmac_f32_e32 v2, s86, v214
	v_cmp_eq_u32_e32 vcc, 0, v22
	v_mov_b32_e32 v14, 0
	s_and_saveexec_b64 s[0:1], vcc
	s_cbranch_execz .LBB0_98
	s_movk_i32 s12, 0x1800
	v_mad_i32_i24 v14, v1, s12, v4
	v_readlane_b32 s56, v252, 16
	v_ashrrev_i32_e32 v15, 31, v14
	v_readlane_b32 s66, v252, 26
	v_readlane_b32 s67, v252, 27
	v_readlane_b32 s57, v252, 17
	v_readlane_b32 s58, v252, 18
	v_lshl_add_u64 v[14:15], v[14:15], 2, s[66:67]
	global_load_dword v14, v[14:15], off
	v_readlane_b32 s59, v252, 19
	v_readlane_b32 s60, v252, 20
	v_readlane_b32 s61, v252, 21
	v_readlane_b32 s62, v252, 22
	v_readlane_b32 s63, v252, 23
	v_readlane_b32 s64, v252, 24
	v_readlane_b32 s65, v252, 25
	v_readlane_b32 s68, v252, 28
	v_readlane_b32 s69, v252, 29
	v_readlane_b32 s70, v252, 30
	v_readlane_b32 s71, v252, 31
	s_branch .LBB0_98

; __device__ __forceinline__ void attn_unit(LAS unsigned char* lds, const Args& A, int b, int h, int qrow0, int nkt) {
;     ...
;     if (map == 0) {
;         float ss = 0.f;
; #pragma unroll
;         for (int i = 0; i < 4; ++i)
; #pragma unroll
;             for (int r = 0; r < 16; ++r) { const float o = O[i][r] * inv - A.lam * ex[(i * 16 + r) * 64 + lane]; O[i][r] = o; ss += o * o; }
.LBB0_706:
	s_andn2_b64 vcc, exec, s[0:1]
	s_waitcnt lgkmcnt(0)
	s_barrier
	s_cbranch_vccnz .LBB0_671
	ds_read2st64_b32 v[80:81], v68 offset1:1
	ds_read2st64_b32 v[82:83], v68 offset0:2 offset1:3
	ds_read2st64_b32 v[84:85], v68 offset0:4 offset1:5
	ds_read2st64_b32 v[86:87], v68 offset0:6 offset1:7
	ds_read2st64_b32 v[88:89], v68 offset0:8 offset1:9
	ds_read2st64_b32 v[90:91], v68 offset0:10 offset1:11
	ds_read2st64_b32 v[92:93], v68 offset0:12 offset1:13
	ds_read2st64_b32 v[94:95], v68 offset0:14 offset1:15
	v_mov_b32_e32 v166, v48
	v_readlane_b32 s0, v253, 16
	v_readlane_b32 s1, v253, 17
	s_lshl_b32 s42, s12, 8
	s_waitcnt lgkmcnt(0)
	v_mov_b32_e32 v65, v80
	v_pk_mul_f32 v[70:71], v[166:167], v[64:65]
	v_mov_b32_e32 v166, v49
	v_mov_b32_e32 v65, v81
	v_pk_mul_f32 v[66:67], v[166:167], v[64:65]
	v_mov_b32_e32 v166, v50
	v_sub_f32_e32 v49, v66, v67
	v_sub_f32_e32 v48, v70, v71
	v_lshlrev_b32_e32 v160, 3, v184
	s_waitcnt lgkmcnt(0)
	v_mov_b32_e32 v65, v82
	v_pk_mul_f32 v[70:71], v[166:167], v[64:65]
	v_mov_b32_e32 v166, v51
	v_mov_b32_e32 v65, v83
	v_pk_mul_f32 v[66:67], v[166:167], v[64:65]
	v_mov_b32_e32 v166, v52
	v_sub_f32_e32 v51, v66, v67
	v_sub_f32_e32 v50, v70, v71
	s_waitcnt lgkmcnt(0)
	v_mov_b32_e32 v65, v84
	v_pk_mul_f32 v[70:71], v[166:167], v[64:65]
	v_mov_b32_e32 v166, v53
	v_mov_b32_e32 v65, v85
	v_pk_mul_f32 v[66:67], v[166:167], v[64:65]
	v_mov_b32_e32 v166, v54
	v_sub_f32_e32 v53, v66, v67
	v_sub_f32_e32 v52, v70, v71
	s_waitcnt lgkmcnt(0)
	v_mov_b32_e32 v65, v86
	v_pk_mul_f32 v[70:71], v[166:167], v[64:65]
	v_mov_b32_e32 v166, v55
	v_mov_b32_e32 v65, v87
	v_pk_mul_f32 v[66:67], v[166:167], v[64:65]
	v_mov_b32_e32 v166, v56
	v_sub_f32_e32 v55, v66, v67
	v_sub_f32_e32 v54, v70, v71
	s_waitcnt lgkmcnt(0)
	v_mov_b32_e32 v65, v88
	v_pk_mul_f32 v[70:71], v[166:167], v[64:65]
	v_mov_b32_e32 v166, v57
	v_mov_b32_e32 v65, v89
	v_pk_mul_f32 v[66:67], v[166:167], v[64:65]
	v_mov_b32_e32 v166, v58
	v_sub_f32_e32 v57, v66, v67
	v_sub_f32_e32 v56, v70, v71
	s_waitcnt lgkmcnt(0)
	v_mov_b32_e32 v65, v90
	v_pk_mul_f32 v[70:71], v[166:167], v[64:65]
	v_mov_b32_e32 v166, v59
	v_mov_b32_e32 v65, v91
	v_pk_mul_f32 v[66:67], v[166:167], v[64:65]
	v_mov_b32_e32 v166, v60
	v_sub_f32_e32 v59, v66, v67
	v_sub_f32_e32 v58, v70, v71
	s_waitcnt lgkmcnt(0)
	v_mov_b32_e32 v65, v92
	v_pk_mul_f32 v[70:71], v[166:167], v[64:65]
	v_mov_b32_e32 v166, v61
	v_mov_b32_e32 v65, v93
	v_pk_mul_f32 v[66:67], v[166:167], v[64:65]
	v_mov_b32_e32 v166, v62
	v_sub_f32_e32 v61, v66, v67
	v_sub_f32_e32 v60, v70, v71
	s_waitcnt lgkmcnt(0)
	v_mov_b32_e32 v65, v94
	v_pk_mul_f32 v[70:71], v[166:167], v[64:65]
	v_mov_b32_e32 v166, v63
	v_mov_b32_e32 v65, v95
	v_pk_mul_f32 v[66:67], v[166:167], v[64:65]
	v_mov_b32_e32 v166, v32
	v_sub_f32_e32 v63, v66, v67
	ds_read2st64_b32 v[66:67], v68 offset0:16 offset1:17
	v_sub_f32_e32 v62, v70, v71
	s_waitcnt lgkmcnt(0)
	v_mov_b32_e32 v65, v66
	v_pk_mul_f32 v[70:71], v[166:167], v[64:65]
	v_mov_b32_e32 v166, v33
	v_sub_f32_e32 v66, v70, v71
	ds_read2st64_b32 v[98:99], v68 offset0:18 offset1:19
	ds_read2st64_b32 v[100:101], v68 offset0:20 offset1:21
	ds_read2st64_b32 v[102:103], v68 offset0:22 offset1:23
	ds_read2st64_b32 v[104:105], v68 offset0:24 offset1:25
	ds_read2st64_b32 v[106:107], v68 offset0:26 offset1:27
	ds_read2st64_b32 v[108:109], v68 offset0:28 offset1:29
	ds_read2st64_b32 v[110:111], v68 offset0:30 offset1:31
	ds_read2st64_b32 v[114:115], v68 offset0:34 offset1:35
	v_mov_b32_e32 v65, v67
	v_pk_mul_f32 v[32:33], v[166:167], v[64:65]
	v_mov_b32_e32 v166, v34
	v_sub_f32_e32 v32, v32, v33
	s_waitcnt lgkmcnt(0)
	v_mov_b32_e32 v65, v98
	v_pk_mul_f32 v[72:73], v[166:167], v[64:65]
	v_mov_b32_e32 v166, v35
	v_mov_b32_e32 v65, v99
	v_pk_mul_f32 v[70:71], v[166:167], v[64:65]
	v_mov_b32_e32 v166, v36
	v_sub_f32_e32 v33, v70, v71
	v_sub_f32_e32 v34, v72, v73
	s_waitcnt lgkmcnt(0)
	v_mov_b32_e32 v65, v100
	v_pk_mul_f32 v[72:73], v[166:167], v[64:65]
	v_mov_b32_e32 v166, v37
	v_mov_b32_e32 v65, v101
	v_pk_mul_f32 v[70:71], v[166:167], v[64:65]
	v_mov_b32_e32 v166, v38
	v_sub_f32_e32 v35, v70, v71
	v_sub_f32_e32 v36, v72, v73
	s_waitcnt lgkmcnt(0)
	v_mov_b32_e32 v65, v102
	v_pk_mul_f32 v[72:73], v[166:167], v[64:65]
	v_mov_b32_e32 v65, v103
	v_mov_b32_e32 v166, v39
	v_pk_mul_f32 v[38:39], v[166:167], v[64:65]
	v_mov_b32_e32 v166, v40
	v_sub_f32_e32 v67, v72, v73
	s_waitcnt lgkmcnt(0)
	v_mov_b32_e32 v65, v104
	v_pk_mul_f32 v[72:73], v[166:167], v[64:65]
	v_mov_b32_e32 v65, v105
	v_mov_b32_e32 v166, v41
	v_pk_mul_f32 v[40:41], v[166:167], v[64:65]
	v_mov_b32_e32 v166, v42
	v_sub_f32_e32 v37, v40, v41
	s_waitcnt lgkmcnt(0)
	v_mov_b32_e32 v65, v106
	v_pk_mul_f32 v[40:41], v[166:167], v[64:65]
	v_mov_b32_e32 v65, v107
	v_mov_b32_e32 v166, v43
	v_pk_mul_f32 v[42:43], v[166:167], v[64:65]
	v_mov_b32_e32 v166, v44
	v_sub_f32_e32 v41, v40, v41
	s_waitcnt lgkmcnt(0)
	v_mov_b32_e32 v65, v108
	v_sub_f32_e32 v40, v42, v43
	v_pk_mul_f32 v[42:43], v[166:167], v[64:65]
	v_mov_b32_e32 v65, v109
	v_mov_b32_e32 v166, v45
	v_pk_mul_f32 v[44:45], v[166:167], v[64:65]
	v_mov_b32_e32 v166, v46
	v_sub_f32_e32 v43, v42, v43
	s_waitcnt lgkmcnt(0)
	v_mov_b32_e32 v65, v110
	v_sub_f32_e32 v42, v44, v45
	v_pk_mul_f32 v[44:45], v[166:167], v[64:65]
	v_mov_b32_e32 v166, v47
	v_mov_b32_e32 v65, v111
	v_pk_mul_f32 v[46:47], v[166:167], v[64:65]
	v_sub_f32_e32 v45, v44, v45
	v_sub_f32_e32 v44, v46, v47
	ds_read2st64_b32 v[46:47], v68 offset0:32 offset1:33
	v_mov_b32_e32 v166, v16
	v_sub_f32_e32 v39, v38, v39
	v_sub_f32_e32 v38, v72, v73
	s_waitcnt lgkmcnt(0)
; __device__ __forceinline__ void attn_unit(LAS unsigned char* lds, const Args& A, int b, int h, int qrow0, int nkt) {
;     ...
;             for (int r = 0; r < 16; ++r) { const float o = O[i][r] * inv - A.lam * ex[(i * 16 + r) * 64 + lane]; O[i][r] = o; ss += o * o; }
;         ss += __shfl_xor(ss, 32);
	v_mov_b32_e32 v65, v46
	v_pk_mul_f32 v[70:71], v[166:167], v[64:65]
	v_mov_b32_e32 v166, v17
	v_sub_f32_e32 v46, v70, v71
	v_mov_b32_e32 v65, v47
	v_pk_mul_f32 v[16:17], v[166:167], v[64:65]
	v_mov_b32_e32 v166, v18
	v_sub_f32_e32 v16, v16, v17
	s_waitcnt lgkmcnt(0)
	v_mov_b32_e32 v65, v114
	v_pk_mul_f32 v[72:73], v[166:167], v[64:65]
	v_mov_b32_e32 v166, v19
	v_mov_b32_e32 v65, v115
	v_pk_mul_f32 v[70:71], v[166:167], v[64:65]
	v_mov_b32_e32 v166, v20
	v_sub_f32_e32 v17, v70, v71
	ds_read2st64_b32 v[116:117], v68 offset0:36 offset1:37
	ds_read2st64_b32 v[118:119], v68 offset0:38 offset1:39
	ds_read2st64_b32 v[120:121], v68 offset0:40 offset1:41
	ds_read2st64_b32 v[122:123], v68 offset0:42 offset1:43
	ds_read2st64_b32 v[124:125], v68 offset0:44 offset1:45
	ds_read2st64_b32 v[126:127], v68 offset0:46 offset1:47
	ds_read2st64_b32 v[128:129], v68 offset0:48 offset1:49
	ds_read2st64_b32 v[130:131], v68 offset0:50 offset1:51
	v_sub_f32_e32 v18, v72, v73
	s_waitcnt lgkmcnt(0)
	v_mov_b32_e32 v65, v116
	v_pk_mul_f32 v[72:73], v[166:167], v[64:65]
	v_mov_b32_e32 v166, v21
	v_mov_b32_e32 v65, v117
	v_pk_mul_f32 v[70:71], v[166:167], v[64:65]
	v_mov_b32_e32 v166, v22
	v_sub_f32_e32 v19, v70, v71
	v_sub_f32_e32 v20, v72, v73
	s_waitcnt lgkmcnt(0)
	v_mov_b32_e32 v65, v118
	v_pk_mul_f32 v[72:73], v[166:167], v[64:65]
	v_mov_b32_e32 v65, v119
	v_mov_b32_e32 v166, v23
	v_pk_mul_f32 v[22:23], v[166:167], v[64:65]
	v_mov_b32_e32 v166, v24
	v_sub_f32_e32 v47, v72, v73
	s_waitcnt lgkmcnt(0)
	v_mov_b32_e32 v65, v120
	v_pk_mul_f32 v[72:73], v[166:167], v[64:65]
	v_mov_b32_e32 v65, v121
	v_mov_b32_e32 v166, v25
	v_pk_mul_f32 v[24:25], v[166:167], v[64:65]
	v_mov_b32_e32 v166, v26
	v_sub_f32_e32 v21, v24, v25
	s_waitcnt lgkmcnt(0)
	v_mov_b32_e32 v65, v122
	v_pk_mul_f32 v[24:25], v[166:167], v[64:65]
	v_mov_b32_e32 v65, v123
	v_mov_b32_e32 v166, v27
	v_pk_mul_f32 v[26:27], v[166:167], v[64:65]
	v_mov_b32_e32 v166, v28
	v_sub_f32_e32 v25, v24, v25
	s_waitcnt lgkmcnt(0)
	v_mov_b32_e32 v65, v124
	v_sub_f32_e32 v24, v26, v27
	v_pk_mul_f32 v[26:27], v[166:167], v[64:65]
	v_mov_b32_e32 v166, v29
	v_mov_b32_e32 v65, v125
	v_pk_mul_f32 v[28:29], v[166:167], v[64:65]
	v_sub_f32_e32 v27, v26, v27
	v_sub_f32_e32 v26, v28, v29
	v_mov_b32_e32 v166, v30
	v_sub_f32_e32 v23, v22, v23
	v_sub_f32_e32 v22, v72, v73
	s_waitcnt lgkmcnt(0)
	v_mov_b32_e32 v65, v126
	v_pk_mul_f32 v[70:71], v[166:167], v[64:65]
	v_mov_b32_e32 v166, v31
	v_mov_b32_e32 v65, v127
	v_pk_mul_f32 v[28:29], v[166:167], v[64:65]
	v_mov_b32_e32 v166, v0
	v_sub_f32_e32 v69, v70, v71
	s_waitcnt lgkmcnt(0)
	v_mov_b32_e32 v65, v128
	v_pk_mul_f32 v[70:71], v[166:167], v[64:65]
	v_mov_b32_e32 v166, v1
	v_mov_b32_e32 v65, v129
	v_pk_mul_f32 v[0:1], v[166:167], v[64:65]
	v_sub_f32_e32 v29, v28, v29
	v_sub_f32_e32 v28, v0, v1
	v_mov_b32_e32 v166, v2
	v_sub_f32_e32 v30, v70, v71
	s_waitcnt lgkmcnt(0)
	v_mov_b32_e32 v65, v130
	v_pk_mul_f32 v[70:71], v[166:167], v[64:65]
	v_mov_b32_e32 v166, v3
	v_mov_b32_e32 v65, v131
	v_pk_mul_f32 v[0:1], v[166:167], v[64:65]
	v_mov_b32_e32 v166, v4
	v_sub_f32_e32 v31, v0, v1
	ds_read2st64_b32 v[132:133], v68 offset0:52 offset1:53
	ds_read2st64_b32 v[134:135], v68 offset0:54 offset1:55
	ds_read2st64_b32 v[136:137], v68 offset0:56 offset1:57
	ds_read2st64_b32 v[138:139], v68 offset0:58 offset1:59
	v_sub_f32_e32 v70, v70, v71
	s_waitcnt lgkmcnt(0)
	v_mov_b32_e32 v65, v132
	v_pk_mul_f32 v[2:3], v[166:167], v[64:65]
	v_mov_b32_e32 v166, v5
	v_mov_b32_e32 v65, v133
	v_pk_mul_f32 v[0:1], v[166:167], v[64:65]
	v_mov_b32_e32 v166, v6
	v_sub_f32_e32 v71, v0, v1
	v_sub_f32_e32 v72, v2, v3
	s_waitcnt lgkmcnt(0)
	v_mov_b32_e32 v65, v134
	v_pk_mul_f32 v[2:3], v[166:167], v[64:65]
	v_mov_b32_e32 v166, v7
	v_mov_b32_e32 v65, v135
	v_pk_mul_f32 v[0:1], v[166:167], v[64:65]
	v_mov_b32_e32 v166, v8
	v_mul_f32_e32 v8, v48, v48
	v_fmac_f32_e32 v8, v49, v49
	v_fmac_f32_e32 v8, v50, v50
	v_fmac_f32_e32 v8, v51, v51
	v_fmac_f32_e32 v8, v52, v52
	v_fmac_f32_e32 v8, v53, v53
	v_fmac_f32_e32 v8, v54, v54
	v_fmac_f32_e32 v8, v55, v55
	v_fmac_f32_e32 v8, v56, v56
	v_fmac_f32_e32 v8, v57, v57
	v_fmac_f32_e32 v8, v58, v58
	v_fmac_f32_e32 v8, v59, v59
	v_fmac_f32_e32 v8, v60, v60
	v_fmac_f32_e32 v8, v61, v61
	v_fmac_f32_e32 v8, v62, v62
	v_fmac_f32_e32 v8, v63, v63
	v_fmac_f32_e32 v8, v66, v66
	v_fmac_f32_e32 v8, v32, v32
	v_fmac_f32_e32 v8, v34, v34
	v_fmac_f32_e32 v8, v33, v33
	v_fmac_f32_e32 v8, v36, v36
	v_fmac_f32_e32 v8, v35, v35
	v_fmac_f32_e32 v8, v67, v67
	v_fmac_f32_e32 v8, v39, v39
	v_fmac_f32_e32 v8, v38, v38
	v_fmac_f32_e32 v8, v37, v37
	v_fmac_f32_e32 v8, v41, v41
	v_fmac_f32_e32 v8, v40, v40
	v_fmac_f32_e32 v8, v43, v43
	v_fmac_f32_e32 v8, v42, v42
	v_fmac_f32_e32 v8, v45, v45
	v_fmac_f32_e32 v8, v44, v44
	v_fmac_f32_e32 v8, v46, v46
	v_fmac_f32_e32 v8, v16, v16
	v_fmac_f32_e32 v8, v18, v18
	v_fmac_f32_e32 v8, v17, v17
	v_sub_f32_e32 v75, v0, v1
	v_fmac_f32_e32 v8, v20, v20
	v_fmac_f32_e32 v8, v19, v19
	v_fmac_f32_e32 v8, v47, v47
	v_fmac_f32_e32 v8, v23, v23
	v_fmac_f32_e32 v8, v22, v22
	s_waitcnt lgkmcnt(0)
	v_mov_b32_e32 v65, v136
	v_fmac_f32_e32 v8, v21, v21
	v_sub_f32_e32 v76, v2, v3
	v_pk_mul_f32 v[2:3], v[166:167], v[64:65]
	v_mov_b32_e32 v166, v9
	v_mov_b32_e32 v65, v137
	v_fmac_f32_e32 v8, v25, v25
	v_pk_mul_f32 v[0:1], v[166:167], v[64:65]
	v_fmac_f32_e32 v8, v24, v24
	v_sub_f32_e32 v73, v0, v1
	v_fmac_f32_e32 v8, v27, v27
	v_fmac_f32_e32 v8, v26, v26
	v_fmac_f32_e32 v8, v69, v69
	v_fmac_f32_e32 v8, v29, v29
	v_fmac_f32_e32 v8, v30, v30
	v_mov_b32_e32 v166, v10
	s_waitcnt lgkmcnt(0)
; __device__ __forceinline__ void attn_unit(LAS unsigned char* lds, const Args& A, int b, int h, int qrow0, int nkt) {
;     ...
;             for (int r = 0; r < 16; ++r) { const float o = O[i][r] * inv - A.lam * ex[(i * 16 + r) * 64 + lane]; O[i][r] = o; ss += o * o; }
;         ss += __shfl_xor(ss, 32);
;         const float rstd = __builtin_amdgcn_rsqf(ss * (1.f / 128.f) + EPSV) * A.omli;
;         bf16_t* dst = A.MIXA + (size_t)(qrow0 + qg * 32 + r32) * DM + h * 128 + 4 * hi;
; #pragma unroll
;         for (int i = 0; i < 4; ++i)
; #pragma unroll
;             for (int rq = 0; rq < 4; ++rq) {
;                 const int d0 = 32 * i + 8 * rq;
;                 const f32x4 gg = *(const f32x4*)(A.subln + d0 + 4 * hi);
	v_mov_b32_e32 v65, v138
	v_fmac_f32_e32 v8, v28, v28
	v_sub_f32_e32 v74, v2, v3
	v_pk_mul_f32 v[2:3], v[166:167], v[64:65]
	v_mov_b32_e32 v166, v11
	v_mov_b32_e32 v65, v139
	v_fmac_f32_e32 v8, v70, v70
	v_pk_mul_f32 v[0:1], v[166:167], v[64:65]
	v_fmac_f32_e32 v8, v31, v31
	v_sub_f32_e32 v10, v0, v1
	ds_read2st64_b32 v[0:1], v68 offset0:60 offset1:61
	v_fmac_f32_e32 v8, v72, v72
	v_fmac_f32_e32 v8, v71, v71
	v_sub_f32_e32 v77, v2, v3
	ds_read2st64_b32 v[2:3], v68 offset0:62 offset1:63
	v_fmac_f32_e32 v8, v76, v76
	v_fmac_f32_e32 v8, v75, v75
	v_fmac_f32_e32 v8, v74, v74
	s_waitcnt lgkmcnt(1)
	v_pk_mul_f32 v[0:1], v[168:169], v[0:1]
	v_fmac_f32_e32 v8, v73, v73
	v_pk_fma_f32 v[4:5], v[12:13], v[64:65], v[0:1] op_sel_hi:[1,0,1] neg_lo:[0,0,1] neg_hi:[0,0,1]
	v_fmac_f32_e32 v8, v77, v77
	v_pk_mul_f32 v[0:1], v[4:5], v[4:5]
	s_waitcnt lgkmcnt(0)
	v_pk_mul_f32 v[2:3], v[168:169], v[2:3]
	v_fmac_f32_e32 v8, v10, v10
	v_pk_fma_f32 v[6:7], v[14:15], v[64:65], v[2:3] op_sel_hi:[1,0,1] neg_lo:[0,0,1] neg_hi:[0,0,1]
	v_add_f32_e32 v0, v8, v0
	v_pk_mul_f32 v[2:3], v[6:7], v[6:7]
	v_add_f32_e32 v0, v0, v1
	v_add_f32_e32 v0, v0, v2
	v_add_f32_e32 v0, v0, v3
	ds_bpermute_b32 v1, v214, v0
	s_waitcnt lgkmcnt(0)
	v_add_f32_e32 v0, v0, v1
	v_fmamk_f32 v0, v0, 0x3c000000, v193
	v_rsq_f32_e32 v0, v0
	s_nop 0
	v_mul_f32_e32 v11, v215, v0
	v_lshlrev_b64 v[0:1], 11, v[172:173]
	v_lshl_add_u64 v[0:1], s[0:1], 0, v[0:1]
	v_lshl_add_u64 v[0:1], v[0:1], 0, s[42:43]
	v_lshl_add_u64 v[8:9], v[0:1], 0, v[160:161]
	global_load_dwordx4 v[80:83], v170, s[4:5]
	global_load_dwordx4 v[84:87], v170, s[4:5] offset:32
	global_load_dwordx4 v[88:91], v170, s[4:5] offset:64
	global_load_dwordx4 v[92:95], v170, s[4:5] offset:96
	global_load_dwordx4 v[96:99], v170, s[4:5] offset:128
	global_load_dwordx4 v[100:103], v170, s[4:5] offset:160
	global_load_dwordx4 v[104:107], v170, s[4:5] offset:192
	global_load_dwordx4 v[108:111], v170, s[4:5] offset:224
	global_load_dwordx4 v[112:115], v170, s[4:5] offset:256
	global_load_dwordx4 v[116:119], v170, s[4:5] offset:288
	global_load_dwordx4 v[120:123], v170, s[4:5] offset:320
	global_load_dwordx4 v[124:127], v170, s[4:5] offset:352
	global_load_dwordx4 v[128:131], v170, s[4:5] offset:384
	global_load_dwordx4 v[132:135], v170, s[4:5] offset:416
	global_load_dwordx4 v[136:139], v170, s[4:5] offset:448
	global_load_dwordx4 v[140:143], v170, s[4:5] offset:480
	s_waitcnt vmcnt(0)
; __device__ __forceinline__ u32x2 pack4(f32x4 v) { u32x2 w; w.x = cvt_pk_bf16(v[0], v[1]); w.y = cvt_pk_bf16(v[2], v[3]); return w; }
; __device__ __forceinline__ void attn_unit(LAS unsigned char* lds, const Args& A, int b, int h, int qrow0, int nkt) {
;     ...
;         const float rstd = __builtin_amdgcn_rsqf(ss * (1.f / 128.f) + EPSV) * A.omli;
;         bf16_t* dst = A.MIXA + (size_t)(qrow0 + qg * 32 + r32) * DM + h * 128 + 4 * hi;
; #pragma unroll
;         for (int i = 0; i < 4; ++i)
; #pragma unroll
;             for (int rq = 0; rq < 4; ++rq) {
;                 const int d0 = 32 * i + 8 * rq;
;                 const f32x4 gg = *(const f32x4*)(A.subln + d0 + 4 * hi);
;                 f32x4 v = {O[i][4 * rq] * rstd * gg[0], O[i][4 * rq + 1] * rstd * gg[1], O[i][4 * rq + 2] * rstd * gg[2], O[i][4 * rq + 3] * rstd * gg[3]};
;                 *(u32x2*)(dst + d0) = pack4(v);
;             }
	v_mul_f32_e32 v12, v48, v11
	v_mul_f32_e32 v10, v10, v11
	v_mul_f32_e32 v4, v4, v11
	v_mul_f32_e32 v0, v80, v12
	v_mul_f32_e32 v12, v49, v11
	v_mul_f32_e32 v1, v81, v12
	v_mul_f32_e32 v12, v50, v11
	v_mul_f32_e32 v2, v82, v12
	v_mul_f32_e32 v12, v51, v11
	v_mul_f32_e32 v3, v83, v12
	v_cvt_pk_bf16_f32 v0, v0, v1
	v_cvt_pk_bf16_f32 v1, v2, v3
	global_store_dwordx2 v[8:9], v[0:1], off
	v_mul_f32_e32 v12, v52, v11
	v_mul_f32_e32 v144, v84, v12
	v_mul_f32_e32 v12, v53, v11
	v_mul_f32_e32 v145, v85, v12
	v_mul_f32_e32 v12, v54, v11
	v_mul_f32_e32 v146, v86, v12
	v_mul_f32_e32 v12, v55, v11
	v_mul_f32_e32 v147, v87, v12
	v_cvt_pk_bf16_f32 v144, v144, v145
	v_cvt_pk_bf16_f32 v145, v146, v147
	global_store_dwordx2 v[8:9], v[144:145], off offset:16
	v_mul_f32_e32 v12, v56, v11
	v_mul_f32_e32 v0, v88, v12
	v_mul_f32_e32 v12, v57, v11
	v_mul_f32_e32 v1, v89, v12
	v_mul_f32_e32 v12, v58, v11
	v_mul_f32_e32 v2, v90, v12
	v_mul_f32_e32 v12, v59, v11
	v_mul_f32_e32 v3, v91, v12
	v_cvt_pk_bf16_f32 v0, v0, v1
	v_cvt_pk_bf16_f32 v1, v2, v3
	global_store_dwordx2 v[8:9], v[0:1], off offset:32
	v_mul_f32_e32 v12, v60, v11
	v_mul_f32_e32 v144, v92, v12
	v_mul_f32_e32 v12, v61, v11
	v_mul_f32_e32 v145, v93, v12
	v_mul_f32_e32 v12, v62, v11
	v_mul_f32_e32 v146, v94, v12
	v_mul_f32_e32 v12, v63, v11
	v_mul_f32_e32 v147, v95, v12
	v_cvt_pk_bf16_f32 v144, v144, v145
	v_cvt_pk_bf16_f32 v145, v146, v147
	global_store_dwordx2 v[8:9], v[144:145], off offset:48
	v_mul_f32_e32 v12, v66, v11
	v_mul_f32_e32 v0, v96, v12
	v_mul_f32_e32 v12, v32, v11
	v_mul_f32_e32 v1, v97, v12
	v_mul_f32_e32 v12, v34, v11
	v_mul_f32_e32 v2, v98, v12
	v_mul_f32_e32 v12, v33, v11
	v_mul_f32_e32 v3, v99, v12
	v_cvt_pk_bf16_f32 v0, v0, v1
	v_cvt_pk_bf16_f32 v1, v2, v3
	global_store_dwordx2 v[8:9], v[0:1], off offset:64
	v_mul_f32_e32 v12, v36, v11
	v_mul_f32_e32 v144, v100, v12
	v_mul_f32_e32 v12, v35, v11
	v_mul_f32_e32 v145, v101, v12
	v_mul_f32_e32 v12, v67, v11
	v_mul_f32_e32 v146, v102, v12
	v_mul_f32_e32 v12, v39, v11
	v_mul_f32_e32 v147, v103, v12
	v_cvt_pk_bf16_f32 v144, v144, v145
	v_cvt_pk_bf16_f32 v145, v146, v147
	global_store_dwordx2 v[8:9], v[144:145], off offset:80
	v_mul_f32_e32 v12, v38, v11
	v_mul_f32_e32 v0, v104, v12
	v_mul_f32_e32 v12, v37, v11
	v_mul_f32_e32 v1, v105, v12
	v_mul_f32_e32 v12, v41, v11
	v_mul_f32_e32 v2, v106, v12
	v_mul_f32_e32 v12, v40, v11
	v_mul_f32_e32 v3, v107, v12
	v_cvt_pk_bf16_f32 v0, v0, v1
	v_cvt_pk_bf16_f32 v1, v2, v3
	global_store_dwordx2 v[8:9], v[0:1], off offset:96
	v_mul_f32_e32 v12, v43, v11
	v_mul_f32_e32 v144, v108, v12
	v_mul_f32_e32 v12, v42, v11
	v_mul_f32_e32 v145, v109, v12
	v_mul_f32_e32 v12, v45, v11
	v_mul_f32_e32 v146, v110, v12
	v_mul_f32_e32 v12, v44, v11
	v_mul_f32_e32 v147, v111, v12
	v_cvt_pk_bf16_f32 v144, v144, v145
	v_cvt_pk_bf16_f32 v145, v146, v147
	global_store_dwordx2 v[8:9], v[144:145], off offset:112
	v_mul_f32_e32 v12, v46, v11
	v_mul_f32_e32 v0, v112, v12
	v_mul_f32_e32 v12, v16, v11
	v_mul_f32_e32 v1, v113, v12
	v_mul_f32_e32 v12, v18, v11
	v_mul_f32_e32 v2, v114, v12
	v_mul_f32_e32 v12, v17, v11
	v_mul_f32_e32 v3, v115, v12
	v_cvt_pk_bf16_f32 v0, v0, v1
	v_cvt_pk_bf16_f32 v1, v2, v3
	global_store_dwordx2 v[8:9], v[0:1], off offset:128
	v_mul_f32_e32 v12, v20, v11
	v_mul_f32_e32 v144, v116, v12
	v_mul_f32_e32 v12, v19, v11
	v_mul_f32_e32 v145, v117, v12
	v_mul_f32_e32 v12, v47, v11
	v_mul_f32_e32 v146, v118, v12
	v_mul_f32_e32 v12, v23, v11
	v_mul_f32_e32 v147, v119, v12
	v_cvt_pk_bf16_f32 v144, v144, v145
	v_cvt_pk_bf16_f32 v145, v146, v147
	global_store_dwordx2 v[8:9], v[144:145], off offset:144
	v_mul_f32_e32 v12, v22, v11
	v_mul_f32_e32 v0, v120, v12
	v_mul_f32_e32 v12, v21, v11
	v_mul_f32_e32 v1, v121, v12
	v_mul_f32_e32 v12, v25, v11
	v_mul_f32_e32 v2, v122, v12
	v_mul_f32_e32 v12, v24, v11
	v_mul_f32_e32 v3, v123, v12
	v_cvt_pk_bf16_f32 v0, v0, v1
	v_cvt_pk_bf16_f32 v1, v2, v3
	global_store_dwordx2 v[8:9], v[0:1], off offset:160
	v_mul_f32_e32 v12, v27, v11
	v_mul_f32_e32 v144, v124, v12
	v_mul_f32_e32 v12, v26, v11
	v_mul_f32_e32 v145, v125, v12
	v_mul_f32_e32 v12, v69, v11
	v_mul_f32_e32 v146, v126, v12
	v_mul_f32_e32 v12, v29, v11
	v_mul_f32_e32 v147, v127, v12
	v_cvt_pk_bf16_f32 v144, v144, v145
	v_cvt_pk_bf16_f32 v145, v146, v147
	global_store_dwordx2 v[8:9], v[144:145], off offset:176
	v_mul_f32_e32 v12, v30, v11
	v_mul_f32_e32 v0, v128, v12
	v_mul_f32_e32 v12, v28, v11
	v_mul_f32_e32 v1, v129, v12
	v_mul_f32_e32 v12, v70, v11
	v_mul_f32_e32 v2, v130, v12
	v_mul_f32_e32 v12, v31, v11
	v_mul_f32_e32 v3, v131, v12
	v_cvt_pk_bf16_f32 v0, v0, v1
	v_cvt_pk_bf16_f32 v1, v2, v3
	global_store_dwordx2 v[8:9], v[0:1], off offset:192
	v_mul_f32_e32 v12, v72, v11
	v_mul_f32_e32 v144, v132, v12
	v_mul_f32_e32 v12, v71, v11
	v_mul_f32_e32 v145, v133, v12
	v_mul_f32_e32 v12, v76, v11
	v_mul_f32_e32 v146, v134, v12
	v_mul_f32_e32 v12, v75, v11
	v_mul_f32_e32 v147, v135, v12
	v_cvt_pk_bf16_f32 v144, v144, v145
	v_cvt_pk_bf16_f32 v145, v146, v147
	global_store_dwordx2 v[8:9], v[144:145], off offset:208
	v_mul_f32_e32 v12, v74, v11
	v_mul_f32_e32 v0, v136, v12
	v_mul_f32_e32 v12, v73, v11
	v_mul_f32_e32 v1, v137, v12
	v_mul_f32_e32 v12, v77, v11
	v_mul_f32_e32 v2, v138, v12
	v_mul_f32_e32 v3, v139, v10
	v_cvt_pk_bf16_f32 v0, v0, v1
	v_cvt_pk_bf16_f32 v1, v2, v3
	global_store_dwordx2 v[8:9], v[0:1], off offset:224
	v_mul_f32_e32 v144, v140, v4
	v_mul_f32_e32 v4, v5, v11
	v_mul_f32_e32 v145, v141, v4
	v_mul_f32_e32 v4, v6, v11
	v_mul_f32_e32 v146, v142, v4
	v_mul_f32_e32 v4, v7, v11
	v_mul_f32_e32 v147, v143, v4
	v_cvt_pk_bf16_f32 v144, v144, v145
	v_cvt_pk_bf16_f32 v145, v146, v147
	global_store_dwordx2 v[8:9], v[144:145], off offset:240
	s_branch .LBB0_671
